# sc1-stores-for-memory-attention-outputs
# speedup vs baseline: 1.0684x; 1.0032x over previous
.LBB0_123:
	s_add_i32 s4, s5, s6
	s_ashr_i32 s5, s4, 31
	s_lshr_b32 s5, s5, 29
	s_add_i32 s5, s4, s5
	s_ashr_i32 s6, s5, 3
	s_lshl_b32 s6, s6, 1
	s_sub_i32 s7, 64, s6
	s_min_i32 s7, s7, 2
	s_abs_i32 s9, s7
	v_cvt_f32_u32_e32 v0, s9
	s_sub_i32 s10, 0, s9
	s_and_b32 s5, s5, -8
	s_sub_i32 s5, s4, s5
	v_rcp_iflag_f32_e32 v0, v0
	s_abs_i32 s8, s5
	s_xor_b32 s4, s5, s7
	s_ashr_i32 s4, s4, 31
	v_mul_f32_e32 v0, 0x4f7ffffe, v0
	v_cvt_u32_f32_e32 v0, v0
	v_mov_b32_e32 v8, v245
	v_cmp_lt_i32_e32 vcc, v234, v228
	v_readfirstlane_b32 s11, v0
	s_mul_i32 s10, s10, s11
	s_mul_hi_u32 s10, s11, s10
	s_add_i32 s11, s11, s10
	s_mul_hi_u32 s10, s8, s11
	s_mul_i32 s11, s10, s9
	s_sub_i32 s8, s8, s11
	s_add_i32 s11, s10, 1
	s_sub_i32 s12, s8, s9
	s_cmp_ge_u32 s8, s9
	s_cselect_b32 s10, s11, s10
	s_cselect_b32 s8, s12, s8
	s_add_i32 s11, s10, 1
	s_cmp_ge_u32 s8, s9
	s_cselect_b32 s8, s11, s10
	s_xor_b32 s8, s8, s4
	s_sub_i32 s4, s8, s4
	s_mul_i32 s7, s4, s7
	s_sub_i32 s5, s5, s7
	s_add_i32 s5, s6, s5
	s_ashr_i32 s6, s5, 31
	s_lshr_b32 s6, s6, 28
	s_add_i32 s6, s5, s6
	s_ashr_i32 s30, s6, 4
	s_and_b32 s6, s6, 0xfffff0
	s_sub_i32 s5, s5, s6
	s_lshl_b32 s10, s30, 8
	s_lshl_b32 s7, s5, 8
	s_ashr_i32 s11, s10, 31
	s_ashr_i32 s31, s30, 31
	s_ashr_i32 s8, s7, 31
	s_lshl_b64 s[10:11], s[10:11], 12
	s_add_u32 s6, s33, s10
	s_waitcnt lgkmcnt(0)
	v_ashrrev_i32_e32 v2, 6, v8
	s_addc_u32 s9, s40, s11
	s_lshl_b32 s4, s4, 8
	v_bfe_u32 v72, v8, 5, 1
	v_lshlrev_b32_e32 v0, 5, v2
	s_ashr_i32 s5, s4, 31
	s_lshl_b64 s[28:29], s[4:5], 1
	v_readfirstlane_b32 s4, v2
	v_or_b32_e32 v2, v0, v72
	v_and_b32_e32 v9, 31, v8
	v_lshrrev_b32_e32 v10, 5, v8
	s_add_u32 s36, s6, s28
	v_ashrrev_i32_e32 v3, 31, v2
	s_addc_u32 s37, s9, s29
	v_lshlrev_b64 v[4:5], 12, v[2:3]
	v_bitop3_b32 v3, v10, v9, 1 bitop3:0x6c
	v_lshl_add_u64 v[4:5], s[36:37], 0, v[4:5]
	v_lshlrev_b32_e32 v96, 4, v3
	v_lshl_add_u64 v[4:5], v[4:5], 0, v[96:97]
	s_lshl_b32 s9, s4, 14
	s_add_i32 s4, s9, 0
	s_mov_b32 s5, m0
	s_mov_b32 m0, s4
	s_nop 0
	global_load_lds_dwordx4 v[4:5], off
	s_mov_b32 m0, s5
	v_or_b32_e32 v4, 2, v2
	v_ashrrev_i32_e32 v5, 31, v4
	v_lshlrev_b64 v[6:7], 12, v[4:5]
	v_bitop3_b32 v3, v4, v9, 3 bitop3:0x6c
	v_lshl_add_u64 v[6:7], s[36:37], 0, v[6:7]
	v_lshlrev_b32_e32 v4, 4, v3
	v_mov_b32_e32 v5, v97
	v_lshl_add_u64 v[4:5], v[6:7], 0, v[4:5]
	s_add_i32 s5, 0, 0x400
	s_add_i32 s4, s9, s5
	s_mov_b32 s6, m0
	s_mov_b32 m0, s4
	s_nop 0
	global_load_lds_dwordx4 v[4:5], off
	s_mov_b32 m0, s6
	v_or_b32_e32 v4, 4, v2
	v_ashrrev_i32_e32 v5, 31, v4
	v_lshlrev_b64 v[6:7], 12, v[4:5]
	v_bitop3_b32 v3, v4, v9, 5 bitop3:0x6c
	v_lshl_add_u64 v[6:7], s[36:37], 0, v[6:7]
	v_lshlrev_b32_e32 v4, 4, v3
	v_mov_b32_e32 v5, v97
	v_lshl_add_u64 v[4:5], v[6:7], 0, v[4:5]
	s_add_i32 s6, 0, 0x800
	s_add_i32 s4, s9, s6
	s_mov_b32 s10, m0
	s_mov_b32 m0, s4
	s_nop 0
	global_load_lds_dwordx4 v[4:5], off
	s_mov_b32 m0, s10
	v_or_b32_e32 v4, 6, v2
	v_ashrrev_i32_e32 v5, 31, v4
	v_lshlrev_b64 v[6:7], 12, v[4:5]
	v_bitop3_b32 v3, v4, v9, 7 bitop3:0x6c
	v_lshl_add_u64 v[6:7], s[36:37], 0, v[6:7]
	v_lshlrev_b32_e32 v4, 4, v3
	v_mov_b32_e32 v5, v97
	v_lshl_add_u64 v[4:5], v[6:7], 0, v[4:5]
	s_add_i32 s4, s9, s18
	s_mov_b32 s10, m0
	s_mov_b32 m0, s4
	s_nop 0
	global_load_lds_dwordx4 v[4:5], off
	s_mov_b32 m0, s10
	v_or_b32_e32 v4, 8, v2
	v_ashrrev_i32_e32 v5, 31, v4
	v_lshlrev_b64 v[6:7], 12, v[4:5]
	v_bitop3_b32 v3, v4, v9, 9 bitop3:0x6c
	v_lshl_add_u64 v[6:7], s[36:37], 0, v[6:7]
	v_lshlrev_b32_e32 v4, 4, v3
	v_mov_b32_e32 v5, v97
	v_lshl_add_u64 v[4:5], v[6:7], 0, v[4:5]
	s_add_i32 s4, 0, 0x1000
	s_add_i32 s10, s9, s4
	s_mov_b32 s11, m0
	s_mov_b32 m0, s10
	s_nop 0
	global_load_lds_dwordx4 v[4:5], off
	s_mov_b32 m0, s11
	v_or_b32_e32 v4, 10, v2
	v_ashrrev_i32_e32 v5, 31, v4
	v_lshlrev_b64 v[6:7], 12, v[4:5]
	v_bitop3_b32 v3, v4, v9, 11 bitop3:0x6c
	v_lshl_add_u64 v[6:7], s[36:37], 0, v[6:7]
	v_lshlrev_b32_e32 v4, 4, v3
	v_mov_b32_e32 v5, v97
	v_lshl_add_u64 v[4:5], v[6:7], 0, v[4:5]
	s_add_i32 s10, s9, s19
	s_mov_b32 s11, m0
	s_mov_b32 m0, s10
	s_nop 0
	global_load_lds_dwordx4 v[4:5], off
	s_mov_b32 m0, s11
	v_or_b32_e32 v4, 12, v2
	v_ashrrev_i32_e32 v5, 31, v4
	v_lshlrev_b64 v[6:7], 12, v[4:5]
	v_bitop3_b32 v3, v4, v9, 13 bitop3:0x6c
	v_lshl_add_u64 v[6:7], s[36:37], 0, v[6:7]
	v_lshlrev_b32_e32 v4, 4, v3
	v_mov_b32_e32 v5, v97
	v_lshl_add_u64 v[4:5], v[6:7], 0, v[4:5]
	s_add_i32 s10, s9, s41
	s_mov_b32 s11, m0
	s_mov_b32 m0, s10
	s_nop 0
	global_load_lds_dwordx4 v[4:5], off
	s_mov_b32 m0, s11
	v_or_b32_e32 v4, 14, v2
	v_ashrrev_i32_e32 v5, 31, v4
	v_lshlrev_b64 v[6:7], 12, v[4:5]
	v_bitop3_b32 v3, v4, v9, 15 bitop3:0x6c
	v_lshl_add_u64 v[6:7], s[36:37], 0, v[6:7]
	v_lshlrev_b32_e32 v4, 4, v3
	v_mov_b32_e32 v5, v97
	v_lshl_add_u64 v[4:5], v[6:7], 0, v[4:5]
	s_add_i32 s10, s9, s42
	s_mov_b32 s11, m0
	s_mov_b32 m0, s10
	s_nop 0
	global_load_lds_dwordx4 v[4:5], off
	s_mov_b32 m0, s11
	v_or_b32_e32 v4, 16, v2
	v_ashrrev_i32_e32 v5, 31, v4
	v_lshlrev_b64 v[4:5], 12, v[4:5]
	v_lshl_add_u64 v[4:5], s[36:37], 0, v[4:5]
	v_lshl_add_u64 v[4:5], v[4:5], 0, v[96:97]
	s_add_i32 s10, s9, s43
	s_mov_b32 s11, m0
	s_mov_b32 m0, s10
	s_nop 0
	global_load_lds_dwordx4 v[4:5], off
	s_mov_b32 m0, s11
	v_or_b32_e32 v4, 18, v2
	v_ashrrev_i32_e32 v5, 31, v4
	v_lshlrev_b64 v[6:7], 12, v[4:5]
	v_bitop3_b32 v3, v4, v9, 3 bitop3:0x6c
	v_lshl_add_u64 v[6:7], s[36:37], 0, v[6:7]
	v_lshlrev_b32_e32 v96, 4, v3
	v_lshl_add_u64 v[4:5], v[6:7], 0, v[96:97]
	s_add_i32 s10, s9, s44
	s_mov_b32 s11, m0
	s_mov_b32 m0, s10
	s_nop 0
	global_load_lds_dwordx4 v[4:5], off
	s_mov_b32 m0, s11
	v_or_b32_e32 v4, 20, v2
	v_ashrrev_i32_e32 v5, 31, v4
	v_lshlrev_b64 v[6:7], 12, v[4:5]
	v_bitop3_b32 v3, v4, v9, 5 bitop3:0x6c
	v_lshl_add_u64 v[6:7], s[36:37], 0, v[6:7]
	v_lshlrev_b32_e32 v96, 4, v3
	v_lshl_add_u64 v[4:5], v[6:7], 0, v[96:97]
	s_add_i32 s10, s9, s45
	s_mov_b32 s11, m0
	s_mov_b32 m0, s10
	s_nop 0
	global_load_lds_dwordx4 v[4:5], off
	s_mov_b32 m0, s11
	v_or_b32_e32 v4, 22, v2
	v_ashrrev_i32_e32 v5, 31, v4
	v_lshlrev_b64 v[6:7], 12, v[4:5]
	v_bitop3_b32 v3, v4, v9, 7 bitop3:0x6c
	v_lshl_add_u64 v[6:7], s[36:37], 0, v[6:7]
	v_lshlrev_b32_e32 v96, 4, v3
	v_lshl_add_u64 v[4:5], v[6:7], 0, v[96:97]
	s_add_i32 s10, s9, s46
	s_mov_b32 s11, m0
	s_mov_b32 m0, s10
	s_nop 0
	global_load_lds_dwordx4 v[4:5], off
	s_mov_b32 m0, s11
	v_or_b32_e32 v4, 24, v2
	v_ashrrev_i32_e32 v5, 31, v4
	v_lshlrev_b64 v[6:7], 12, v[4:5]
	v_bitop3_b32 v3, v4, v9, 9 bitop3:0x6c
	v_lshl_add_u64 v[6:7], s[36:37], 0, v[6:7]
	v_lshlrev_b32_e32 v96, 4, v3
	v_lshl_add_u64 v[4:5], v[6:7], 0, v[96:97]
	s_add_i32 s10, s9, s47
	s_mov_b32 s11, m0
	s_mov_b32 m0, s10
	s_nop 0
	global_load_lds_dwordx4 v[4:5], off
	s_mov_b32 m0, s11
	v_or_b32_e32 v4, 26, v2
	v_ashrrev_i32_e32 v5, 31, v4
	v_lshlrev_b64 v[6:7], 12, v[4:5]
	v_bitop3_b32 v3, v4, v9, 11 bitop3:0x6c
	v_lshl_add_u64 v[6:7], s[36:37], 0, v[6:7]
	v_lshlrev_b32_e32 v96, 4, v3
	v_lshl_add_u64 v[4:5], v[6:7], 0, v[96:97]
	s_add_i32 s10, s9, s48
	s_mov_b32 s11, m0
	s_mov_b32 m0, s10
	s_nop 0
	global_load_lds_dwordx4 v[4:5], off
	s_mov_b32 m0, s11
	v_or_b32_e32 v4, 28, v2
	v_ashrrev_i32_e32 v5, 31, v4
	v_lshlrev_b64 v[6:7], 12, v[4:5]
	v_bitop3_b32 v3, v4, v9, 13 bitop3:0x6c
	v_lshl_add_u64 v[6:7], s[36:37], 0, v[6:7]
	v_lshlrev_b32_e32 v96, 4, v3
	v_or_b32_e32 v2, 30, v2
	v_lshl_add_u64 v[4:5], v[6:7], 0, v[96:97]
	v_ashrrev_i32_e32 v3, 31, v2
	s_add_i32 s10, s9, s49
	s_mov_b32 s11, m0
	s_mov_b32 m0, s10
	s_nop 0
	global_load_lds_dwordx4 v[4:5], off
	s_mov_b32 m0, s11
	v_lshlrev_b64 v[4:5], 12, v[2:3]
	v_bitop3_b32 v2, v2, v9, 15 bitop3:0x6c
	v_lshl_add_u64 v[4:5], s[36:37], 0, v[4:5]
	v_lshlrev_b32_e32 v96, 4, v2
	v_lshl_add_u64 v[2:3], v[4:5], 0, v[96:97]
	s_add_i32 s9, s9, s50
	s_mov_b32 s10, m0
	s_mov_b32 m0, s9
	s_nop 0
	global_load_lds_dwordx4 v[2:3], off
	s_mov_b32 m0, s10
	s_lshl_b64 s[10:11], s[30:31], 12
	s_add_u32 s38, s10, s7
	v_ashrrev_i32_e32 v1, 31, v0
	s_addc_u32 s39, s11, s8
	v_lshl_add_u64 v[0:1], s[38:39], 0, v[0:1]
	v_or_b32_e32 v0, v0, v9
	v_lshlrev_b64 v[0:1], 11, v[0:1]
	v_lshl_add_u64 v[0:1], s[24:25], 0, v[0:1]
	v_lshl_add_u64 v[0:1], v[0:1], 0, s[28:29]
	v_lshlrev_b32_e32 v96, 4, v72
	v_lshl_add_u64 v[0:1], v[0:1], 0, v[96:97]
	global_load_dwordx4 v[142:145], v[0:1], off
	global_load_dwordx4 v[138:141], v[0:1], off offset:32
	global_load_dwordx4 v[134:137], v[0:1], off offset:64
	global_load_dwordx4 v[130:133], v[0:1], off offset:96
	global_load_dwordx4 v[126:129], v[0:1], off offset:128
	global_load_dwordx4 v[122:125], v[0:1], off offset:160
	global_load_dwordx4 v[118:121], v[0:1], off offset:192
	global_load_dwordx4 v[114:117], v[0:1], off offset:224
	global_load_dwordx4 v[60:63], v[0:1], off offset:256
	global_load_dwordx4 v[56:59], v[0:1], off offset:288
	global_load_dwordx4 v[52:55], v[0:1], off offset:320
	global_load_dwordx4 v[48:51], v[0:1], off offset:352
	global_load_dwordx4 v[44:47], v[0:1], off offset:384
	global_load_dwordx4 v[40:43], v[0:1], off offset:416
	global_load_dwordx4 v[36:39], v[0:1], off offset:448
	global_load_dwordx4 v[32:35], v[0:1], off offset:480
	v_and_b32_e32 v73, 15, v8
	v_bitop3_b32 v0, v10, v73, 1 bitop3:0x6c
	v_lshl_add_u32 v162, v9, 9, 0
	v_lshlrev_b32_e32 v161, 4, v0
	v_add_u32_e32 v89, v162, v161
	s_waitcnt vmcnt(0)
	s_barrier
	ds_read_b128 v[0:3], v89
	ds_read_b128 v[16:19], v89 offset:16384
	s_waitcnt vmcnt(0) lgkmcnt(0)
	v_mfma_f32_32x32x16_bf16 v[0:15], v[0:3], v[142:145], 0
	v_bitop3_b32 v64, v72, v73, 2 bitop3:0x36
	v_lshlrev_b32_e32 v160, 4, v64
	v_add_u32_e32 v86, v162, v160
	ds_read_b128 v[64:67], v86
	ds_read_b128 v[68:71], v86 offset:16384
	s_add_i32 s2, s2, 1
	s_waitcnt lgkmcnt(2)
	v_mfma_f32_32x32x16_bf16 v[16:31], v[16:19], v[142:145], 0
	s_waitcnt vmcnt(14) lgkmcnt(1)
	v_mfma_f32_32x32x16_bf16 v[0:15], v[64:67], v[138:141], v[0:15]
	v_bitop3_b32 v64, v72, v73, 4 bitop3:0x36
	v_lshlrev_b32_e32 v159, 4, v64
	v_add_u32_e32 v87, v162, v159
	s_waitcnt lgkmcnt(0)
	v_mfma_f32_32x32x16_bf16 v[16:31], v[68:71], v[138:141], v[16:31]
	ds_read_b128 v[64:67], v87
	ds_read_b128 v[68:71], v87 offset:16384
	s_waitcnt vmcnt(13) lgkmcnt(1)
	v_mfma_f32_32x32x16_bf16 v[0:15], v[64:67], v[134:137], v[0:15]
	v_bitop3_b32 v64, v72, v73, 6 bitop3:0x36
	v_lshlrev_b32_e32 v158, 4, v64
	v_add_u32_e32 v88, v162, v158
	s_waitcnt lgkmcnt(0)
	v_mfma_f32_32x32x16_bf16 v[16:31], v[68:71], v[134:137], v[16:31]
	ds_read_b128 v[64:67], v88
	ds_read_b128 v[68:71], v88 offset:16384
	s_waitcnt vmcnt(12) lgkmcnt(1)
	v_mfma_f32_32x32x16_bf16 v[0:15], v[64:67], v[130:133], v[0:15]
	v_bitop3_b32 v64, v72, v73, 8 bitop3:0x36
	v_lshlrev_b32_e32 v157, 4, v64
	v_add_u32_e32 v90, v162, v157
	s_waitcnt lgkmcnt(0)
	v_mfma_f32_32x32x16_bf16 v[16:31], v[68:71], v[130:133], v[16:31]
	ds_read_b128 v[64:67], v90
	ds_read_b128 v[68:71], v90 offset:16384
	s_waitcnt vmcnt(11) lgkmcnt(1)
	v_mfma_f32_32x32x16_bf16 v[0:15], v[64:67], v[126:129], v[0:15]
	v_bitop3_b32 v64, v72, v73, 10 bitop3:0x36
	v_lshlrev_b32_e32 v156, 4, v64
	v_add_u32_e32 v91, v162, v156
	s_waitcnt lgkmcnt(0)
	v_mfma_f32_32x32x16_bf16 v[16:31], v[68:71], v[126:129], v[16:31]
	ds_read_b128 v[64:67], v91
	ds_read_b128 v[68:71], v91 offset:16384
	s_waitcnt vmcnt(10) lgkmcnt(1)
	v_mfma_f32_32x32x16_bf16 v[0:15], v[64:67], v[122:125], v[0:15]
	v_bitop3_b32 v64, v72, v73, 12 bitop3:0x36
	v_lshlrev_b32_e32 v155, 4, v64
	v_add_u32_e32 v92, v162, v155
	s_waitcnt lgkmcnt(0)
	v_mfma_f32_32x32x16_bf16 v[16:31], v[68:71], v[122:125], v[16:31]
	ds_read_b128 v[64:67], v92
	ds_read_b128 v[68:71], v92 offset:16384
	s_waitcnt vmcnt(9) lgkmcnt(1)
	v_mfma_f32_32x32x16_bf16 v[0:15], v[64:67], v[118:121], v[0:15]
	v_bitop3_b32 v64, v72, v73, 14 bitop3:0x36
	v_lshlrev_b32_e32 v154, 4, v64
	v_add_u32_e32 v93, v162, v154
	s_waitcnt lgkmcnt(0)
	v_mfma_f32_32x32x16_bf16 v[16:31], v[68:71], v[118:121], v[16:31]
	ds_read_b128 v[64:67], v93
	ds_read_b128 v[68:71], v93 offset:16384
	s_waitcnt vmcnt(8) lgkmcnt(1)
	v_mfma_f32_32x32x16_bf16 v[0:15], v[64:67], v[114:117], v[0:15]
	v_bitop3_b32 v64, v72, v73, 16 bitop3:0x36
	v_lshlrev_b32_e32 v153, 4, v64
	v_add_u32_e32 v95, v162, v153
	s_waitcnt lgkmcnt(0)
	v_mfma_f32_32x32x16_bf16 v[16:31], v[68:71], v[114:117], v[16:31]
	ds_read_b128 v[64:67], v95
	ds_read_b128 v[68:71], v95 offset:16384
	s_waitcnt vmcnt(7) lgkmcnt(1)
	v_mfma_f32_32x32x16_bf16 v[0:15], v[64:67], v[60:63], v[0:15]
	v_bitop3_b32 v64, v72, v73, 18 bitop3:0x36
	v_lshlrev_b32_e32 v152, 4, v64
	v_add_u32_e32 v94, v162, v152
	s_waitcnt lgkmcnt(0)
	v_mfma_f32_32x32x16_bf16 v[16:31], v[68:71], v[60:63], v[16:31]
	ds_read_b128 v[64:67], v94
	ds_read_b128 v[68:71], v94 offset:16384
	s_waitcnt vmcnt(6) lgkmcnt(1)
	v_mfma_f32_32x32x16_bf16 v[0:15], v[64:67], v[56:59], v[0:15]
	v_bitop3_b32 v64, v72, v73, 20 bitop3:0x36
	v_lshlrev_b32_e32 v151, 4, v64
	v_add_u32_e32 v85, v162, v151
	s_waitcnt lgkmcnt(0)
	v_mfma_f32_32x32x16_bf16 v[16:31], v[68:71], v[56:59], v[16:31]
	ds_read_b128 v[64:67], v85
	ds_read_b128 v[68:71], v85 offset:16384
	s_waitcnt vmcnt(5) lgkmcnt(1)
	v_mfma_f32_32x32x16_bf16 v[0:15], v[64:67], v[52:55], v[0:15]
	v_bitop3_b32 v64, v72, v73, 22 bitop3:0x36
	v_lshlrev_b32_e32 v150, 4, v64
	v_add_u32_e32 v84, v162, v150
	s_waitcnt lgkmcnt(0)
	v_mfma_f32_32x32x16_bf16 v[16:31], v[68:71], v[52:55], v[16:31]
	ds_read_b128 v[64:67], v84
	ds_read_b128 v[68:71], v84 offset:16384
	s_waitcnt vmcnt(4) lgkmcnt(1)
	v_mfma_f32_32x32x16_bf16 v[0:15], v[64:67], v[48:51], v[0:15]
	v_bitop3_b32 v64, v72, v73, 24 bitop3:0x36
	v_lshlrev_b32_e32 v149, 4, v64
	v_add_u32_e32 v83, v162, v149
	s_waitcnt lgkmcnt(0)
	v_mfma_f32_32x32x16_bf16 v[16:31], v[68:71], v[48:51], v[16:31]
	ds_read_b128 v[64:67], v83
	ds_read_b128 v[68:71], v83 offset:16384
	s_waitcnt vmcnt(3) lgkmcnt(1)
	v_mfma_f32_32x32x16_bf16 v[0:15], v[64:67], v[44:47], v[0:15]
	v_bitop3_b32 v64, v72, v73, 26 bitop3:0x36
	v_lshlrev_b32_e32 v148, 4, v64
	v_add_u32_e32 v82, v162, v148
	s_waitcnt lgkmcnt(0)
	v_mfma_f32_32x32x16_bf16 v[16:31], v[68:71], v[44:47], v[16:31]
	ds_read_b128 v[64:67], v82
	ds_read_b128 v[68:71], v82 offset:16384
	s_waitcnt vmcnt(2) lgkmcnt(1)
	v_mfma_f32_32x32x16_bf16 v[0:15], v[64:67], v[40:43], v[0:15]
	v_bitop3_b32 v64, v72, v73, 28 bitop3:0x36
	v_lshlrev_b32_e32 v147, 4, v64
	v_add_u32_e32 v81, v162, v147
	s_waitcnt lgkmcnt(0)
	v_mfma_f32_32x32x16_bf16 v[16:31], v[68:71], v[40:43], v[16:31]
	ds_read_b128 v[64:67], v81
	ds_read_b128 v[68:71], v81 offset:16384
	s_waitcnt vmcnt(1) lgkmcnt(1)
	v_mfma_f32_32x32x16_bf16 v[0:15], v[64:67], v[36:39], v[0:15]
	v_bitop3_b32 v64, v72, v73, 30 bitop3:0x36
	v_lshlrev_b32_e32 v146, 4, v64
	v_add_u32_e32 v80, v162, v146
	s_waitcnt lgkmcnt(0)
	v_mfma_f32_32x32x16_bf16 v[16:31], v[68:71], v[36:39], v[16:31]
	ds_read_b128 v[64:67], v80
	ds_read_b128 v[68:71], v80 offset:16384
	s_waitcnt vmcnt(0) lgkmcnt(1)
	v_mfma_f32_32x32x16_bf16 v[0:15], v[64:67], v[32:35], v[0:15]
	s_waitcnt lgkmcnt(0)
	v_mfma_f32_32x32x16_bf16 v[16:31], v[68:71], v[32:35], v[16:31]
	s_nop 9
	v_max_f32_e32 v65, v0, v0
	v_max_f32_e32 v66, v1, v1
	v_max_f32_e32 v67, v3, v3
	v_max_f32_e32 v64, v16, v16
	v_max_f32_e32 v64, v65, v64
	v_max_f32_e32 v65, v17, v17
	v_max_f32_e32 v65, v66, v65
	v_max3_f32 v64, v64, s35, v65
	v_max_f32_e32 v65, v18, v18
	v_max_f32_e32 v66, v2, v2
	v_max_f32_e32 v65, v66, v65
	v_max_f32_e32 v66, v19, v19
	v_max_f32_e32 v66, v67, v66
	v_max3_f32 v64, v64, v65, v66
	v_max_f32_e32 v65, v20, v20
	v_max_f32_e32 v66, v4, v4
	v_max_f32_e32 v65, v66, v65
	v_max_f32_e32 v66, v21, v21
	v_max_f32_e32 v67, v5, v5
	v_max_f32_e32 v66, v67, v66
	v_max3_f32 v64, v64, v65, v66
	v_max_f32_e32 v65, v22, v22
	v_max_f32_e32 v66, v6, v6
	v_max_f32_e32 v65, v66, v65
	v_max_f32_e32 v66, v23, v23
	v_max_f32_e32 v67, v7, v7
	v_max_f32_e32 v66, v67, v66
	v_max3_f32 v64, v64, v65, v66
	v_max_f32_e32 v65, v24, v24
	v_max_f32_e32 v66, v8, v8
	v_max_f32_e32 v65, v66, v65
	v_max_f32_e32 v66, v25, v25
	v_max_f32_e32 v67, v9, v9
	v_max_f32_e32 v66, v67, v66
	v_max3_f32 v64, v64, v65, v66
	v_max_f32_e32 v65, v26, v26
	v_max_f32_e32 v66, v10, v10
	v_max_f32_e32 v65, v66, v65
	v_max_f32_e32 v66, v27, v27
	v_max_f32_e32 v67, v11, v11
	v_max_f32_e32 v66, v67, v66
	v_max3_f32 v64, v64, v65, v66
	v_max_f32_e32 v65, v28, v28
	v_max_f32_e32 v66, v12, v12
	v_max_f32_e32 v65, v66, v65
	v_max_f32_e32 v66, v29, v29
	v_max_f32_e32 v67, v13, v13
	v_max_f32_e32 v66, v67, v66
	v_max3_f32 v64, v64, v65, v66
	v_max_f32_e32 v65, v30, v30
	v_max_f32_e32 v66, v14, v14
	v_max_f32_e32 v65, v66, v65
	v_max_f32_e32 v66, v31, v31
	v_max_f32_e32 v67, v15, v15
	v_max_f32_e32 v66, v67, v66
	v_max3_f32 v64, v64, v65, v66
	v_mov_b32_e32 v65, v64
	s_nop 1
	v_permlane32_swap_b32_e32 v64, v65
	v_max_f32_e32 v65, v65, v65
	v_max_f32_e32 v64, v64, v64
	v_max_f32_e32 v96, v64, v65
	v_sub_f32_e32 v0, v0, v96
	v_sub_f32_e32 v16, v16, v96
	v_exp_f32_e32 v0, v0
	v_exp_f32_e32 v16, v16
	v_sub_f32_e32 v1, v1, v96
	v_sub_f32_e32 v17, v17, v96
	v_exp_f32_e32 v1, v1
	v_exp_f32_e32 v17, v17
	v_sub_f32_e32 v2, v2, v96
	v_sub_f32_e32 v18, v18, v96
	v_exp_f32_e32 v2, v2
	v_exp_f32_e32 v18, v18
	v_sub_f32_e32 v3, v3, v96
	v_sub_f32_e32 v19, v19, v96
	v_exp_f32_e32 v3, v3
	v_exp_f32_e32 v19, v19
	v_sub_f32_e32 v4, v4, v96
	v_sub_f32_e32 v20, v20, v96
	v_add_f32_e32 v98, v16, v0
	v_exp_f32_e32 v4, v4
	v_exp_f32_e32 v20, v20
	v_sub_f32_e32 v5, v5, v96
	v_sub_f32_e32 v21, v21, v96
	v_add_f32_e32 v99, v17, v1
	v_exp_f32_e32 v5, v5
	v_exp_f32_e32 v21, v21
	v_sub_f32_e32 v6, v6, v96
	v_sub_f32_e32 v22, v22, v96
	v_cvt_pk_bf16_f32 v76, v0, v1
	v_add_f32_e32 v0, 0, v98
	v_add_f32_e32 v100, v18, v2
	v_exp_f32_e32 v6, v6
	v_exp_f32_e32 v22, v22
	v_sub_f32_e32 v7, v7, v96
	v_sub_f32_e32 v23, v23, v96
	v_add_f32_e32 v0, v99, v0
	v_add_f32_e32 v101, v19, v3
	v_exp_f32_e32 v7, v7
	v_exp_f32_e32 v23, v23
	v_sub_f32_e32 v8, v8, v96
	v_sub_f32_e32 v24, v24, v96
	v_add_f32_e32 v0, v100, v0
	v_add_f32_e32 v102, v20, v4
	v_exp_f32_e32 v8, v8
	v_exp_f32_e32 v24, v24
	v_sub_f32_e32 v9, v9, v96
	v_sub_f32_e32 v25, v25, v96
	v_add_f32_e32 v0, v101, v0
	v_add_f32_e32 v103, v21, v5
	v_exp_f32_e32 v9, v9
	v_exp_f32_e32 v25, v25
	v_sub_f32_e32 v10, v10, v96
	v_sub_f32_e32 v26, v26, v96
	v_add_f32_e32 v0, v102, v0
	v_add_f32_e32 v104, v22, v6
	v_exp_f32_e32 v10, v10
	v_exp_f32_e32 v26, v26
	v_sub_f32_e32 v11, v11, v96
	v_sub_f32_e32 v27, v27, v96
	v_add_f32_e32 v0, v103, v0
	v_add_f32_e32 v105, v23, v7
	v_exp_f32_e32 v11, v11
	v_exp_f32_e32 v27, v27
	v_sub_f32_e32 v12, v12, v96
	v_sub_f32_e32 v28, v28, v96
	v_add_f32_e32 v0, v104, v0
	v_add_f32_e32 v106, v24, v8
	v_exp_f32_e32 v12, v12
	v_exp_f32_e32 v28, v28
	v_sub_f32_e32 v13, v13, v96
	v_sub_f32_e32 v29, v29, v96
	v_add_f32_e32 v0, v105, v0
	v_add_f32_e32 v107, v25, v9
	v_exp_f32_e32 v13, v13
	v_exp_f32_e32 v29, v29
	v_sub_f32_e32 v14, v14, v96
	v_sub_f32_e32 v30, v30, v96
	v_add_f32_e32 v0, v106, v0
	v_add_f32_e32 v108, v26, v10
	v_exp_f32_e32 v14, v14
	v_exp_f32_e32 v30, v30
	v_sub_f32_e32 v15, v15, v96
	v_sub_f32_e32 v31, v31, v96
	v_add_f32_e32 v0, v107, v0
	v_add_f32_e32 v109, v27, v11
	v_exp_f32_e32 v15, v15
	v_exp_f32_e32 v31, v31
	v_add_f32_e32 v0, v108, v0
	v_add_f32_e32 v110, v28, v12
	v_add_f32_e32 v0, v109, v0
	v_add_f32_e32 v111, v29, v13
	v_add_f32_e32 v0, v110, v0
	v_add_f32_e32 v112, v30, v14
	v_add_f32_e32 v0, v111, v0
	v_add_f32_e32 v113, v31, v15
	v_add_f32_e32 v0, v112, v0
	v_cvt_pk_bf16_f32 v77, v2, v3
	v_cvt_pk_bf16_f32 v78, v4, v5
	v_cvt_pk_bf16_f32 v79, v6, v7
	v_add_f32_e32 v98, v113, v0
	ds_read_b128 v[0:3], v89 offset:32768
	ds_read_b128 v[4:7], v89 offset:49152
	v_cvt_pk_bf16_f32 v68, v16, v17
	v_cvt_pk_bf16_f32 v69, v18, v19
	v_cvt_pk_bf16_f32 v70, v20, v21
	v_cvt_pk_bf16_f32 v71, v22, v23
	v_cvt_pk_bf16_f32 v72, v8, v9
	v_cvt_pk_bf16_f32 v73, v10, v11
	v_cvt_pk_bf16_f32 v74, v12, v13
	v_cvt_pk_bf16_f32 v75, v14, v15
	v_cvt_pk_bf16_f32 v64, v24, v25
	v_cvt_pk_bf16_f32 v65, v26, v27
	v_cvt_pk_bf16_f32 v66, v28, v29
	v_cvt_pk_bf16_f32 v67, v30, v31
	s_waitcnt lgkmcnt(1)
	v_mfma_f32_32x32x16_bf16 v[16:31], v[0:3], v[142:145], 0
	ds_read_b128 v[100:103], v86 offset:32768
	ds_read_b128 v[104:107], v86 offset:49152
	s_waitcnt lgkmcnt(2)
	v_mfma_f32_32x32x16_bf16 v[0:15], v[4:7], v[142:145], 0
	s_waitcnt lgkmcnt(1)
	v_mfma_f32_32x32x16_bf16 v[16:31], v[100:103], v[138:141], v[16:31]
	s_waitcnt lgkmcnt(0)
	v_mfma_f32_32x32x16_bf16 v[0:15], v[104:107], v[138:141], v[0:15]
	ds_read_b128 v[100:103], v87 offset:32768
	ds_read_b128 v[104:107], v87 offset:49152
	s_waitcnt lgkmcnt(1)
	v_mfma_f32_32x32x16_bf16 v[16:31], v[100:103], v[134:137], v[16:31]
	ds_read_b128 v[100:103], v88 offset:32768
	ds_read_b128 v[86:89], v88 offset:49152
	s_waitcnt lgkmcnt(2)
	v_mfma_f32_32x32x16_bf16 v[0:15], v[104:107], v[134:137], v[0:15]
	s_waitcnt lgkmcnt(1)
	v_mfma_f32_32x32x16_bf16 v[16:31], v[100:103], v[130:133], v[16:31]
	s_waitcnt lgkmcnt(0)
	v_mfma_f32_32x32x16_bf16 v[0:15], v[86:89], v[130:133], v[0:15]
	ds_read_b128 v[86:89], v90 offset:32768
	ds_read_b128 v[100:103], v90 offset:49152
	s_waitcnt lgkmcnt(1)
	v_mfma_f32_32x32x16_bf16 v[16:31], v[86:89], v[126:129], v[16:31]
	s_waitcnt lgkmcnt(0)
	v_mfma_f32_32x32x16_bf16 v[0:15], v[100:103], v[126:129], v[0:15]
	ds_read_b128 v[86:89], v91 offset:32768
	ds_read_b128 v[100:103], v91 offset:49152
	s_waitcnt lgkmcnt(1)
	v_mfma_f32_32x32x16_bf16 v[16:31], v[86:89], v[122:125], v[16:31]
	s_waitcnt lgkmcnt(0)
	v_mfma_f32_32x32x16_bf16 v[0:15], v[100:103], v[122:125], v[0:15]
	ds_read_b128 v[86:89], v92 offset:32768
	ds_read_b128 v[100:103], v92 offset:49152
	s_waitcnt lgkmcnt(1)
	v_mfma_f32_32x32x16_bf16 v[16:31], v[86:89], v[118:121], v[16:31]
	ds_read_b128 v[86:89], v93 offset:32768
	ds_read_b128 v[90:93], v93 offset:49152
	s_waitcnt lgkmcnt(2)
	v_mfma_f32_32x32x16_bf16 v[0:15], v[100:103], v[118:121], v[0:15]
	s_waitcnt lgkmcnt(1)
	v_mfma_f32_32x32x16_bf16 v[16:31], v[86:89], v[114:117], v[16:31]
	s_waitcnt lgkmcnt(0)
	v_mfma_f32_32x32x16_bf16 v[0:15], v[90:93], v[114:117], v[0:15]
	ds_read_b128 v[86:89], v95 offset:32768
	ds_read_b128 v[90:93], v95 offset:49152
	s_waitcnt lgkmcnt(1)
	v_mfma_f32_32x32x16_bf16 v[16:31], v[86:89], v[60:63], v[16:31]
	s_waitcnt lgkmcnt(0)
	v_mfma_f32_32x32x16_bf16 v[0:15], v[90:93], v[60:63], v[0:15]
	ds_read_b128 v[86:89], v94 offset:32768
	ds_read_b128 v[90:93], v94 offset:49152
	s_waitcnt lgkmcnt(1)
	v_mfma_f32_32x32x16_bf16 v[16:31], v[86:89], v[56:59], v[16:31]
	s_waitcnt lgkmcnt(0)
	v_mfma_f32_32x32x16_bf16 v[0:15], v[90:93], v[56:59], v[0:15]
	ds_read_b128 v[86:89], v85 offset:32768
	ds_read_b128 v[90:93], v85 offset:49152
	s_waitcnt lgkmcnt(1)
	v_mfma_f32_32x32x16_bf16 v[16:31], v[86:89], v[52:55], v[16:31]
	s_waitcnt lgkmcnt(0)
	v_mfma_f32_32x32x16_bf16 v[0:15], v[90:93], v[52:55], v[0:15]
	ds_read_b128 v[86:89], v84 offset:32768
	ds_read_b128 v[90:93], v84 offset:49152
	s_waitcnt lgkmcnt(1)
	v_mfma_f32_32x32x16_bf16 v[16:31], v[86:89], v[48:51], v[16:31]
	s_waitcnt lgkmcnt(0)
	v_mfma_f32_32x32x16_bf16 v[0:15], v[90:93], v[48:51], v[0:15]
	ds_read_b128 v[84:87], v83 offset:32768
	ds_read_b128 v[88:91], v83 offset:49152
	s_waitcnt lgkmcnt(1)
	v_mfma_f32_32x32x16_bf16 v[16:31], v[84:87], v[44:47], v[16:31]
	s_waitcnt lgkmcnt(0)
	v_mfma_f32_32x32x16_bf16 v[0:15], v[88:91], v[44:47], v[0:15]
	ds_read_b128 v[84:87], v82 offset:32768
	ds_read_b128 v[88:91], v82 offset:49152
	s_waitcnt lgkmcnt(1)
	v_mfma_f32_32x32x16_bf16 v[16:31], v[84:87], v[40:43], v[16:31]
	s_waitcnt lgkmcnt(0)
	v_mfma_f32_32x32x16_bf16 v[0:15], v[88:91], v[40:43], v[0:15]
	ds_read_b128 v[82:85], v81 offset:32768
	ds_read_b128 v[86:89], v81 offset:49152
	s_waitcnt lgkmcnt(1)
	v_mfma_f32_32x32x16_bf16 v[16:31], v[82:85], v[36:39], v[16:31]
	s_waitcnt lgkmcnt(0)
	v_mfma_f32_32x32x16_bf16 v[0:15], v[86:89], v[36:39], v[0:15]
	ds_read_b128 v[82:85], v80 offset:32768
	ds_read_b128 v[86:89], v80 offset:49152
	s_waitcnt lgkmcnt(1)
	v_mfma_f32_32x32x16_bf16 v[16:31], v[82:85], v[32:35], v[16:31]
	s_waitcnt lgkmcnt(0)
	v_mfma_f32_32x32x16_bf16 v[0:15], v[86:89], v[32:35], v[0:15]
	s_nop 9
	v_sub_f32_e32 v16, v16, v96
	v_exp_f32_e32 v16, v16
	v_sub_f32_e32 v17, v17, v96
	v_exp_f32_e32 v17, v17
	v_sub_f32_e32 v18, v18, v96
	v_exp_f32_e32 v18, v18
	v_sub_f32_e32 v19, v19, v96
	v_sub_f32_e32 v0, v0, v96
	v_exp_f32_e32 v0, v0
	v_sub_f32_e32 v1, v1, v96
	v_exp_f32_e32 v1, v1
	v_sub_f32_e32 v2, v2, v96
	v_exp_f32_e32 v2, v2
	v_sub_f32_e32 v3, v3, v96
	v_exp_f32_e32 v19, v19
	v_exp_f32_e32 v3, v3
	v_sub_f32_e32 v20, v20, v96
	v_sub_f32_e32 v4, v4, v96
	v_add_f32_e32 v99, v16, v0
	v_exp_f32_e32 v20, v20
	v_exp_f32_e32 v4, v4
	v_sub_f32_e32 v21, v21, v96
	v_sub_f32_e32 v5, v5, v96
	v_add_f32_e32 v100, v17, v1
	v_exp_f32_e32 v21, v21
	v_exp_f32_e32 v5, v5
	v_sub_f32_e32 v22, v22, v96
	v_sub_f32_e32 v6, v6, v96
	v_cvt_pk_bf16_f32 v84, v0, v1
	v_add_f32_e32 v0, v98, v99
	v_add_f32_e32 v101, v18, v2
	v_exp_f32_e32 v22, v22
	v_exp_f32_e32 v6, v6
	v_sub_f32_e32 v23, v23, v96
	v_sub_f32_e32 v7, v7, v96
	v_add_f32_e32 v0, v100, v0
	v_add_f32_e32 v102, v19, v3
	v_exp_f32_e32 v23, v23
	v_exp_f32_e32 v7, v7
	v_sub_f32_e32 v24, v24, v96
	v_sub_f32_e32 v8, v8, v96
	v_add_f32_e32 v0, v101, v0
	v_add_f32_e32 v103, v20, v4
	v_exp_f32_e32 v24, v24
	v_exp_f32_e32 v8, v8
	v_sub_f32_e32 v25, v25, v96
	v_sub_f32_e32 v9, v9, v96
	v_add_f32_e32 v0, v102, v0
	v_add_f32_e32 v104, v21, v5
	v_exp_f32_e32 v25, v25
	v_exp_f32_e32 v9, v9
	v_sub_f32_e32 v26, v26, v96
	v_sub_f32_e32 v10, v10, v96
	v_add_f32_e32 v0, v103, v0
	v_add_f32_e32 v105, v22, v6
	v_exp_f32_e32 v26, v26
	v_exp_f32_e32 v10, v10
	v_sub_f32_e32 v27, v27, v96
	v_sub_f32_e32 v11, v11, v96
	v_add_f32_e32 v0, v104, v0
	v_add_f32_e32 v106, v23, v7
	v_exp_f32_e32 v27, v27
	v_exp_f32_e32 v11, v11
	v_sub_f32_e32 v28, v28, v96
	v_sub_f32_e32 v12, v12, v96
	v_add_f32_e32 v0, v105, v0
	v_add_f32_e32 v107, v24, v8
	v_exp_f32_e32 v28, v28
	v_exp_f32_e32 v12, v12
	v_sub_f32_e32 v29, v29, v96
	v_sub_f32_e32 v13, v13, v96
	v_add_f32_e32 v0, v106, v0
	v_add_f32_e32 v108, v25, v9
	v_exp_f32_e32 v29, v29
	v_exp_f32_e32 v13, v13
	v_sub_f32_e32 v30, v30, v96
	v_sub_f32_e32 v14, v14, v96
	v_add_f32_e32 v0, v107, v0
	v_add_f32_e32 v109, v26, v10
	v_exp_f32_e32 v30, v30
	v_exp_f32_e32 v14, v14
	v_sub_f32_e32 v31, v31, v96
	v_sub_f32_e32 v15, v15, v96
	v_add_f32_e32 v0, v108, v0
	v_add_f32_e32 v110, v27, v11
	v_exp_f32_e32 v31, v31
	v_exp_f32_e32 v15, v15
	v_add_f32_e32 v0, v109, v0
	v_add_f32_e32 v111, v28, v12
	v_add_f32_e32 v0, v110, v0
	v_add_f32_e32 v112, v29, v13
	v_add_f32_e32 v0, v111, v0
	v_add_f32_e32 v113, v30, v14
	v_add_f32_e32 v0, v112, v0
	v_add_f32_e32 v163, v31, v15
	v_add_f32_e32 v0, v113, v0
	v_add_u32_e32 v99, 0x10000, v162
	v_add_u32_e32 v98, 0x14000, v162
	v_cvt_pk_bf16_f32 v86, v4, v5
	v_add_f32_e32 v163, v163, v0
	v_add_u32_e32 v0, v99, v161
	v_add_u32_e32 v4, v98, v161
	v_cvt_pk_bf16_f32 v85, v2, v3
	v_cvt_pk_bf16_f32 v87, v6, v7
	ds_read_b128 v[0:3], v0
	ds_read_b128 v[4:7], v4
	v_add_u32_e32 v100, v99, v160
	v_add_u32_e32 v104, v98, v160
	ds_read_b128 v[100:103], v100
	ds_read_b128 v[104:107], v104
	v_cvt_pk_bf16_f32 v92, v16, v17
	v_cvt_pk_bf16_f32 v93, v18, v19
	v_cvt_pk_bf16_f32 v94, v20, v21
	v_cvt_pk_bf16_f32 v95, v22, v23
	v_cvt_pk_bf16_f32 v88, v24, v25
	v_cvt_pk_bf16_f32 v89, v26, v27
	v_cvt_pk_bf16_f32 v90, v28, v29
	v_cvt_pk_bf16_f32 v91, v30, v31
	v_cvt_pk_bf16_f32 v80, v8, v9
	v_cvt_pk_bf16_f32 v81, v10, v11
	v_cvt_pk_bf16_f32 v82, v12, v13
	v_cvt_pk_bf16_f32 v83, v14, v15
	s_waitcnt lgkmcnt(3)
	v_mfma_f32_32x32x16_bf16 v[16:31], v[0:3], v[142:145], 0
	s_waitcnt lgkmcnt(2)
	v_mfma_f32_32x32x16_bf16 v[0:15], v[4:7], v[142:145], 0
	s_waitcnt lgkmcnt(1)
	v_mfma_f32_32x32x16_bf16 v[16:31], v[100:103], v[138:141], v[16:31]
	v_add_u32_e32 v100, v99, v159
	ds_read_b128 v[100:103], v100
	s_waitcnt lgkmcnt(1)
	v_mfma_f32_32x32x16_bf16 v[0:15], v[104:107], v[138:141], v[0:15]
	v_add_u32_e32 v104, v98, v159
	ds_read_b128 v[104:107], v104
	s_waitcnt lgkmcnt(1)
	v_mfma_f32_32x32x16_bf16 v[16:31], v[100:103], v[134:137], v[16:31]
	v_add_u32_e32 v100, v99, v158
	ds_read_b128 v[100:103], v100
	s_waitcnt lgkmcnt(1)
	v_mfma_f32_32x32x16_bf16 v[0:15], v[104:107], v[134:137], v[0:15]
	v_add_u32_e32 v104, v98, v158
	ds_read_b128 v[104:107], v104
	s_waitcnt lgkmcnt(1)
	v_mfma_f32_32x32x16_bf16 v[16:31], v[100:103], v[130:133], v[16:31]
	v_add_u32_e32 v100, v99, v157
	ds_read_b128 v[100:103], v100
	s_waitcnt lgkmcnt(1)
	v_mfma_f32_32x32x16_bf16 v[0:15], v[104:107], v[130:133], v[0:15]
	v_add_u32_e32 v104, v98, v157
	ds_read_b128 v[104:107], v104
	s_waitcnt lgkmcnt(1)
	v_mfma_f32_32x32x16_bf16 v[16:31], v[100:103], v[126:129], v[16:31]
	v_add_u32_e32 v100, v99, v156
	ds_read_b128 v[100:103], v100
	s_waitcnt lgkmcnt(1)
	v_mfma_f32_32x32x16_bf16 v[0:15], v[104:107], v[126:129], v[0:15]
	v_add_u32_e32 v104, v98, v156
	ds_read_b128 v[104:107], v104
	s_waitcnt lgkmcnt(1)
	v_mfma_f32_32x32x16_bf16 v[16:31], v[100:103], v[122:125], v[16:31]
	v_add_u32_e32 v100, v99, v155
	ds_read_b128 v[100:103], v100
	s_waitcnt lgkmcnt(1)
	v_mfma_f32_32x32x16_bf16 v[0:15], v[104:107], v[122:125], v[0:15]
	v_add_u32_e32 v104, v98, v155
	ds_read_b128 v[104:107], v104
	s_waitcnt lgkmcnt(1)
	v_mfma_f32_32x32x16_bf16 v[16:31], v[100:103], v[118:121], v[16:31]
	v_add_u32_e32 v100, v99, v154
	ds_read_b128 v[100:103], v100
	s_waitcnt lgkmcnt(1)
	v_mfma_f32_32x32x16_bf16 v[0:15], v[104:107], v[118:121], v[0:15]
	v_add_u32_e32 v104, v98, v154
	ds_read_b128 v[104:107], v104
	s_waitcnt lgkmcnt(1)
	v_mfma_f32_32x32x16_bf16 v[16:31], v[100:103], v[114:117], v[16:31]
	v_add_u32_e32 v100, v99, v153
	ds_read_b128 v[100:103], v100
	s_waitcnt lgkmcnt(1)
	v_mfma_f32_32x32x16_bf16 v[0:15], v[104:107], v[114:117], v[0:15]
	v_add_u32_e32 v104, v98, v153
	ds_read_b128 v[104:107], v104
	s_waitcnt lgkmcnt(1)
	v_mfma_f32_32x32x16_bf16 v[16:31], v[100:103], v[60:63], v[16:31]
	v_add_u32_e32 v100, v99, v152
	ds_read_b128 v[100:103], v100
	s_waitcnt lgkmcnt(1)
	v_mfma_f32_32x32x16_bf16 v[0:15], v[104:107], v[60:63], v[0:15]
	v_add_u32_e32 v104, v98, v152
	ds_read_b128 v[104:107], v104
	s_waitcnt lgkmcnt(1)
	v_mfma_f32_32x32x16_bf16 v[16:31], v[100:103], v[56:59], v[16:31]
	v_add_u32_e32 v100, v99, v151
	ds_read_b128 v[100:103], v100
	s_waitcnt lgkmcnt(1)
	v_mfma_f32_32x32x16_bf16 v[0:15], v[104:107], v[56:59], v[0:15]
	v_add_u32_e32 v104, v98, v151
	ds_read_b128 v[104:107], v104
	s_waitcnt lgkmcnt(1)
	v_mfma_f32_32x32x16_bf16 v[16:31], v[100:103], v[52:55], v[16:31]
	v_add_u32_e32 v100, v99, v150
	ds_read_b128 v[100:103], v100
	s_waitcnt lgkmcnt(1)
	v_mfma_f32_32x32x16_bf16 v[0:15], v[104:107], v[52:55], v[0:15]
	v_add_u32_e32 v104, v98, v150
	ds_read_b128 v[104:107], v104
	s_waitcnt lgkmcnt(1)
	v_mfma_f32_32x32x16_bf16 v[16:31], v[100:103], v[48:51], v[16:31]
	v_add_u32_e32 v100, v99, v149
	ds_read_b128 v[100:103], v100
	s_waitcnt lgkmcnt(1)
	v_mfma_f32_32x32x16_bf16 v[0:15], v[104:107], v[48:51], v[0:15]
	v_add_u32_e32 v104, v98, v149
	ds_read_b128 v[104:107], v104
	s_waitcnt lgkmcnt(1)
	v_mfma_f32_32x32x16_bf16 v[16:31], v[100:103], v[44:47], v[16:31]
	v_add_u32_e32 v100, v99, v148
	ds_read_b128 v[100:103], v100
	s_waitcnt lgkmcnt(1)
	v_mfma_f32_32x32x16_bf16 v[0:15], v[104:107], v[44:47], v[0:15]
	v_add_u32_e32 v104, v98, v148
	ds_read_b128 v[104:107], v104
	s_waitcnt lgkmcnt(1)
	v_mfma_f32_32x32x16_bf16 v[16:31], v[100:103], v[40:43], v[16:31]
	v_add_u32_e32 v100, v99, v147
	ds_read_b128 v[100:103], v100
	v_add_u32_e32 v99, v99, v146
	s_waitcnt lgkmcnt(1)
	v_mfma_f32_32x32x16_bf16 v[0:15], v[104:107], v[40:43], v[0:15]
	v_add_u32_e32 v104, v98, v147
	ds_read_b128 v[104:107], v104
	v_add_u32_e32 v98, v98, v146
	s_waitcnt lgkmcnt(1)
	v_mfma_f32_32x32x16_bf16 v[16:31], v[100:103], v[36:39], v[16:31]
	ds_read_b128 v[100:103], v99
	s_waitcnt lgkmcnt(1)
	v_mfma_f32_32x32x16_bf16 v[0:15], v[104:107], v[36:39], v[0:15]
	ds_read_b128 v[104:107], v98
	s_waitcnt lgkmcnt(1)
	v_mfma_f32_32x32x16_bf16 v[16:31], v[100:103], v[32:35], v[16:31]
	s_waitcnt lgkmcnt(0)
	v_mfma_f32_32x32x16_bf16 v[0:15], v[104:107], v[32:35], v[0:15]
	s_nop 9
	v_sub_f32_e32 v16, v16, v96
	v_exp_f32_e32 v16, v16
	v_sub_f32_e32 v17, v17, v96
	v_exp_f32_e32 v17, v17
	v_sub_f32_e32 v18, v18, v96
	v_exp_f32_e32 v18, v18
	v_sub_f32_e32 v19, v19, v96
	v_sub_f32_e32 v0, v0, v96
	v_exp_f32_e32 v0, v0
	v_sub_f32_e32 v1, v1, v96
	v_exp_f32_e32 v1, v1
	v_sub_f32_e32 v2, v2, v96
	v_exp_f32_e32 v2, v2
	v_sub_f32_e32 v3, v3, v96
	v_exp_f32_e32 v19, v19
	v_exp_f32_e32 v3, v3
	v_sub_f32_e32 v20, v20, v96
	v_sub_f32_e32 v4, v4, v96
	v_add_f32_e32 v164, v16, v0
	v_exp_f32_e32 v20, v20
	v_exp_f32_e32 v4, v4
	v_sub_f32_e32 v21, v21, v96
	v_sub_f32_e32 v5, v5, v96
	v_add_f32_e32 v165, v17, v1
	v_exp_f32_e32 v21, v21
	v_exp_f32_e32 v5, v5
	v_sub_f32_e32 v22, v22, v96
	v_sub_f32_e32 v6, v6, v96
	v_cvt_pk_bf16_f32 v102, v0, v1
	v_add_f32_e32 v0, v163, v164
	v_add_f32_e32 v166, v18, v2
	v_exp_f32_e32 v22, v22
	v_exp_f32_e32 v6, v6
	v_sub_f32_e32 v23, v23, v96
	v_sub_f32_e32 v7, v7, v96
	v_add_f32_e32 v0, v165, v0
	v_add_f32_e32 v167, v19, v3
	v_exp_f32_e32 v23, v23
	v_exp_f32_e32 v7, v7
	v_sub_f32_e32 v24, v24, v96
	v_sub_f32_e32 v8, v8, v96
	v_add_f32_e32 v0, v166, v0
	v_add_f32_e32 v168, v20, v4
	v_exp_f32_e32 v24, v24
	v_exp_f32_e32 v8, v8
	v_sub_f32_e32 v25, v25, v96
	v_sub_f32_e32 v9, v9, v96
	v_add_f32_e32 v0, v167, v0
	v_add_f32_e32 v169, v21, v5
	v_exp_f32_e32 v25, v25
	v_exp_f32_e32 v9, v9
	v_sub_f32_e32 v26, v26, v96
	v_sub_f32_e32 v10, v10, v96
	v_add_f32_e32 v0, v168, v0
	v_add_f32_e32 v170, v22, v6
	v_exp_f32_e32 v26, v26
	v_exp_f32_e32 v10, v10
	v_sub_f32_e32 v27, v27, v96
	v_sub_f32_e32 v11, v11, v96
	v_add_f32_e32 v0, v169, v0
	v_add_f32_e32 v171, v23, v7
	v_exp_f32_e32 v27, v27
	v_exp_f32_e32 v11, v11
	v_sub_f32_e32 v28, v28, v96
	v_sub_f32_e32 v12, v12, v96
	v_add_f32_e32 v0, v170, v0
	v_add_f32_e32 v172, v24, v8
	v_exp_f32_e32 v28, v28
	v_exp_f32_e32 v12, v12
	v_sub_f32_e32 v29, v29, v96
	v_sub_f32_e32 v13, v13, v96
	v_add_f32_e32 v0, v171, v0
	v_add_f32_e32 v173, v25, v9
	v_exp_f32_e32 v29, v29
	v_exp_f32_e32 v13, v13
	v_sub_f32_e32 v30, v30, v96
	v_sub_f32_e32 v14, v14, v96
	v_add_f32_e32 v0, v172, v0
	v_add_f32_e32 v174, v26, v10
	v_exp_f32_e32 v30, v30
	v_exp_f32_e32 v14, v14
	v_sub_f32_e32 v31, v31, v96
	v_sub_f32_e32 v15, v15, v96
	v_add_f32_e32 v0, v173, v0
	v_add_f32_e32 v175, v27, v11
	v_exp_f32_e32 v31, v31
	v_exp_f32_e32 v15, v15
	v_add_f32_e32 v0, v174, v0
	v_add_f32_e32 v176, v28, v12
	v_add_f32_e32 v0, v175, v0
	v_add_f32_e32 v177, v29, v13
	v_add_f32_e32 v0, v176, v0
	v_add_f32_e32 v178, v30, v14
	v_add_f32_e32 v0, v177, v0
	v_add_f32_e32 v179, v31, v15
	v_add_f32_e32 v0, v178, v0
	v_add_u32_e32 v164, 0x18000, v162
	v_add_u32_e32 v162, 0x1c000, v162
	v_cvt_pk_bf16_f32 v104, v4, v5
	v_add_f32_e32 v163, v179, v0
	v_add_u32_e32 v0, v164, v161
	v_add_u32_e32 v4, v162, v161
	v_cvt_pk_bf16_f32 v103, v2, v3
	v_cvt_pk_bf16_f32 v105, v6, v7
	ds_read_b128 v[0:3], v0
	ds_read_b128 v[4:7], v4
	v_cvt_pk_bf16_f32 v110, v16, v17
	v_cvt_pk_bf16_f32 v111, v18, v19
	v_cvt_pk_bf16_f32 v112, v20, v21
	v_cvt_pk_bf16_f32 v113, v22, v23
	v_cvt_pk_bf16_f32 v106, v24, v25
	v_cvt_pk_bf16_f32 v107, v26, v27
	v_cvt_pk_bf16_f32 v108, v28, v29
	v_cvt_pk_bf16_f32 v109, v30, v31
	v_cvt_pk_bf16_f32 v98, v8, v9
	v_cvt_pk_bf16_f32 v99, v10, v11
	v_cvt_pk_bf16_f32 v100, v12, v13
	v_cvt_pk_bf16_f32 v101, v14, v15
	s_waitcnt lgkmcnt(1)
	v_mfma_f32_32x32x16_bf16 v[16:31], v[0:3], v[142:145], 0
	s_waitcnt lgkmcnt(0)
	v_mfma_f32_32x32x16_bf16 v[0:15], v[4:7], v[142:145], 0
	v_add_u32_e32 v142, v164, v160
	v_add_u32_e32 v160, v162, v160
	ds_read_b128 v[142:145], v142
	ds_read_b128 v[166:169], v160
	s_waitcnt lgkmcnt(1)
	v_mfma_f32_32x32x16_bf16 v[16:31], v[142:145], v[138:141], v[16:31]
	v_add_u32_e32 v142, v162, v159
	ds_read_b128 v[142:145], v142
	s_waitcnt lgkmcnt(1)
	v_mfma_f32_32x32x16_bf16 v[0:15], v[166:169], v[138:141], v[0:15]
	v_add_u32_e32 v138, v164, v159
	ds_read_b128 v[138:141], v138
	s_waitcnt lgkmcnt(0)
	v_mfma_f32_32x32x16_bf16 v[16:31], v[138:141], v[134:137], v[16:31]
	v_add_u32_e32 v138, v162, v158
	ds_read_b128 v[138:141], v138
	v_mfma_f32_32x32x16_bf16 v[0:15], v[142:145], v[134:137], v[0:15]
	v_add_u32_e32 v134, v164, v158
	ds_read_b128 v[134:137], v134
	s_waitcnt lgkmcnt(0)
	v_mfma_f32_32x32x16_bf16 v[16:31], v[134:137], v[130:133], v[16:31]
	v_add_u32_e32 v134, v162, v157
	ds_read_b128 v[134:137], v134
	v_mfma_f32_32x32x16_bf16 v[0:15], v[138:141], v[130:133], v[0:15]
	v_add_u32_e32 v130, v164, v157
	ds_read_b128 v[130:133], v130
	s_waitcnt lgkmcnt(0)
	v_mfma_f32_32x32x16_bf16 v[16:31], v[130:133], v[126:129], v[16:31]
	v_add_u32_e32 v130, v162, v156
	ds_read_b128 v[130:133], v130
	v_mfma_f32_32x32x16_bf16 v[0:15], v[134:137], v[126:129], v[0:15]
	v_add_u32_e32 v126, v164, v156
	ds_read_b128 v[126:129], v126
	v_mov_b32_e32 v134, v245
	s_waitcnt lgkmcnt(0)
	v_mfma_f32_32x32x16_bf16 v[16:31], v[126:129], v[122:125], v[16:31]
	v_add_u32_e32 v126, v162, v155
	ds_read_b128 v[126:129], v126
	v_mfma_f32_32x32x16_bf16 v[0:15], v[130:133], v[122:125], v[0:15]
	v_add_u32_e32 v122, v164, v155
	ds_read_b128 v[122:125], v122
	s_waitcnt lgkmcnt(0)
	v_mfma_f32_32x32x16_bf16 v[16:31], v[122:125], v[118:121], v[16:31]
	v_add_u32_e32 v122, v162, v154
	ds_read_b128 v[122:125], v122
	v_mfma_f32_32x32x16_bf16 v[0:15], v[126:129], v[118:121], v[0:15]
	v_add_u32_e32 v118, v164, v154
	ds_read_b128 v[118:121], v118
	s_waitcnt lgkmcnt(0)
	v_mfma_f32_32x32x16_bf16 v[16:31], v[118:121], v[114:117], v[16:31]
	v_add_u32_e32 v118, v162, v153
	ds_read_b128 v[118:121], v118
	v_mfma_f32_32x32x16_bf16 v[0:15], v[122:125], v[114:117], v[0:15]
	v_add_u32_e32 v114, v164, v153
	ds_read_b128 v[114:117], v114
	s_waitcnt lgkmcnt(0)
	v_mfma_f32_32x32x16_bf16 v[16:31], v[114:117], v[60:63], v[16:31]
	v_add_u32_e32 v114, v162, v152
	ds_read_b128 v[114:117], v114
	v_mfma_f32_32x32x16_bf16 v[0:15], v[118:121], v[60:63], v[0:15]
	v_add_u32_e32 v60, v164, v152
	ds_read_b128 v[60:63], v60
	s_waitcnt lgkmcnt(0)
	v_mfma_f32_32x32x16_bf16 v[16:31], v[60:63], v[56:59], v[16:31]
	v_add_u32_e32 v60, v162, v151
	ds_read_b128 v[60:63], v60
	v_mfma_f32_32x32x16_bf16 v[0:15], v[114:117], v[56:59], v[0:15]
	v_add_u32_e32 v56, v164, v151
	ds_read_b128 v[56:59], v56
	s_waitcnt lgkmcnt(0)
	v_mfma_f32_32x32x16_bf16 v[16:31], v[56:59], v[52:55], v[16:31]
	v_add_u32_e32 v56, v162, v150
	ds_read_b128 v[56:59], v56
	v_mfma_f32_32x32x16_bf16 v[0:15], v[60:63], v[52:55], v[0:15]
	v_add_u32_e32 v52, v164, v150
	ds_read_b128 v[52:55], v52
	s_waitcnt lgkmcnt(0)
	v_mfma_f32_32x32x16_bf16 v[16:31], v[52:55], v[48:51], v[16:31]
	v_add_u32_e32 v52, v162, v149
	ds_read_b128 v[52:55], v52
	v_mfma_f32_32x32x16_bf16 v[0:15], v[56:59], v[48:51], v[0:15]
	v_add_u32_e32 v48, v164, v149
	ds_read_b128 v[48:51], v48
	s_waitcnt lgkmcnt(0)
	v_mfma_f32_32x32x16_bf16 v[16:31], v[48:51], v[44:47], v[16:31]
	v_add_u32_e32 v48, v162, v148
	ds_read_b128 v[48:51], v48
	v_mfma_f32_32x32x16_bf16 v[0:15], v[52:55], v[44:47], v[0:15]
	v_add_u32_e32 v44, v164, v148
	ds_read_b128 v[44:47], v44
	s_waitcnt lgkmcnt(0)
	v_mfma_f32_32x32x16_bf16 v[16:31], v[44:47], v[40:43], v[16:31]
	v_add_u32_e32 v44, v162, v147
	ds_read_b128 v[44:47], v44
	v_mfma_f32_32x32x16_bf16 v[0:15], v[48:51], v[40:43], v[0:15]
	v_add_u32_e32 v40, v164, v147
	ds_read_b128 v[40:43], v40
	s_waitcnt lgkmcnt(0)
	v_mfma_f32_32x32x16_bf16 v[16:31], v[40:43], v[36:39], v[16:31]
	v_add_u32_e32 v40, v162, v146
	ds_read_b128 v[40:43], v40
	v_mfma_f32_32x32x16_bf16 v[0:15], v[44:47], v[36:39], v[0:15]
	v_add_u32_e32 v36, v164, v146
	ds_read_b128 v[36:39], v36
	s_waitcnt lgkmcnt(0)
	s_barrier
	v_mfma_f32_32x32x16_bf16 v[0:15], v[40:43], v[32:35], v[0:15]
	v_mfma_f32_32x32x16_bf16 v[16:31], v[36:39], v[32:35], v[16:31]
	s_nop 10
	v_sub_f32_e32 v0, v0, v96
	v_exp_f32_e32 v33, v0
	v_sub_f32_e32 v10, v10, v96
	v_sub_f32_e32 v12, v12, v96
	v_sub_f32_e32 v14, v14, v96
	v_sub_f32_e32 v0, v17, v96
	v_exp_f32_e32 v35, v0
	v_sub_f32_e32 v0, v1, v96
	v_exp_f32_e32 v36, v0
	v_sub_f32_e32 v0, v18, v96
	v_exp_f32_e32 v38, v0
	v_sub_f32_e32 v0, v2, v96
	v_exp_f32_e32 v39, v0
	v_sub_f32_e32 v0, v19, v96
	v_exp_f32_e32 v41, v0
	v_sub_f32_e32 v0, v3, v96
	v_exp_f32_e32 v42, v0
	v_sub_f32_e32 v0, v20, v96
	v_exp_f32_e32 v44, v0
	v_sub_f32_e32 v0, v4, v96
	v_exp_f32_e32 v45, v0
	v_sub_f32_e32 v0, v21, v96
	v_exp_f32_e32 v47, v0
	v_sub_f32_e32 v0, v5, v96
	v_exp_f32_e32 v48, v0
	v_sub_f32_e32 v0, v22, v96
	v_exp_f32_e32 v1, v0
	v_sub_f32_e32 v0, v6, v96
	v_exp_f32_e32 v3, v0
	v_sub_f32_e32 v0, v23, v96
	v_sub_f32_e32 v2, v7, v96
	v_sub_f32_e32 v6, v24, v96
	v_exp_f32_e32 v0, v0
	v_exp_f32_e32 v2, v2
	v_exp_f32_e32 v7, v6
	v_sub_f32_e32 v6, v8, v96
	v_exp_f32_e32 v17, v6
	v_sub_f32_e32 v6, v25, v96
	v_exp_f32_e32 v6, v6
	v_sub_f32_e32 v18, v26, v96
	v_exp_f32_e32 v21, v10
	v_sub_f32_e32 v10, v27, v96
	v_exp_f32_e32 v19, v18
	v_exp_f32_e32 v18, v10
	v_sub_f32_e32 v22, v28, v96
	v_exp_f32_e32 v25, v12
	v_sub_f32_e32 v12, v29, v96
	v_pk_add_f32 v[4:5], v[0:1], v[2:3]
	v_exp_f32_e32 v23, v22
	v_exp_f32_e32 v22, v12
	v_sub_f32_e32 v26, v30, v96
	v_exp_f32_e32 v29, v14
	v_sub_f32_e32 v14, v31, v96
	v_pk_mov_b32 v[0:1], v[0:1], v[0:1] op_sel:[1,0]
	v_sub_f32_e32 v16, v16, v96
	v_sub_f32_e32 v8, v9, v96
	v_exp_f32_e32 v27, v26
	v_exp_f32_e32 v26, v14
	v_cvt_pk_bf16_f32 v129, v0, v1
	v_pk_mov_b32 v[0:1], v[2:3], v[2:3] op_sel:[1,0]
	v_exp_f32_e32 v32, v16
	v_exp_f32_e32 v16, v8
	v_sub_f32_e32 v10, v11, v96
	v_cvt_pk_bf16_f32 v121, v0, v1
	v_pk_mov_b32 v[0:1], v[6:7], v[6:7] op_sel:[1,0]
	v_exp_f32_e32 v20, v10
	v_sub_f32_e32 v12, v13, v96
	v_cvt_pk_bf16_f32 v122, v0, v1
	v_pk_mov_b32 v[0:1], v[18:19], v[18:19] op_sel:[1,0]
	v_exp_f32_e32 v24, v12
	v_sub_f32_e32 v14, v15, v96
	v_cvt_pk_bf16_f32 v123, v0, v1
	v_pk_mov_b32 v[0:1], v[22:23], v[22:23] op_sel:[1,0]
	v_exp_f32_e32 v28, v14
	v_cvt_pk_bf16_f32 v124, v0, v1
	v_pk_mov_b32 v[0:1], v[26:27], v[26:27] op_sel:[1,0]
	v_add_f32_e32 v34, v32, v33
	v_cvt_pk_bf16_f32 v125, v0, v1
	v_pk_mov_b32 v[0:1], v[16:17], v[16:17] op_sel:[1,0]
	v_add_f32_e32 v37, v35, v36
	v_cvt_pk_bf16_f32 v114, v0, v1
	v_pk_mov_b32 v[0:1], v[20:21], v[20:21] op_sel:[1,0]
	v_add_f32_e32 v40, v38, v39
	v_cvt_pk_bf16_f32 v115, v0, v1
	v_pk_mov_b32 v[0:1], v[24:25], v[24:25] op_sel:[1,0]
	v_add_f32_e32 v43, v41, v42
	v_cvt_pk_bf16_f32 v116, v0, v1
	v_pk_mov_b32 v[0:1], v[28:29], v[28:29] op_sel:[1,0]
	v_add_f32_e32 v46, v44, v45
	v_cvt_pk_bf16_f32 v117, v0, v1
	v_add_f32_e32 v0, v163, v34
	v_add_f32_e32 v0, v37, v0
	v_add_f32_e32 v0, v40, v0
	v_add_f32_e32 v0, v43, v0
	v_add_f32_e32 v49, v47, v48
	v_add_f32_e32 v0, v46, v0
	v_add_f32_e32 v0, v49, v0
	v_add_f32_e32 v0, v5, v0
	v_pk_add_f32 v[8:9], v[6:7], v[16:17]
	v_add_f32_e32 v0, v4, v0
	v_add_f32_e32 v0, v9, v0
	v_pk_add_f32 v[10:11], v[18:19], v[20:21]
	v_add_f32_e32 v0, v8, v0
	v_add_f32_e32 v0, v11, v0
	v_pk_add_f32 v[12:13], v[22:23], v[24:25]
	v_add_f32_e32 v0, v10, v0
	v_add_f32_e32 v0, v13, v0
	v_pk_add_f32 v[14:15], v[26:27], v[28:29]
	v_add_f32_e32 v0, v12, v0
	v_add_f32_e32 v0, v15, v0
	v_add_f32_e32 v1, v14, v0
	v_cndmask_b32_e32 v0, v227, v234, vcc
	v_lshlrev_b32_e32 v0, 2, v0
	v_ashrrev_i32_e32 v5, 6, v134
	ds_bpermute_b32 v4, v0, v1
	v_lshlrev_b32_e32 v0, 5, v5
	v_bfe_u32 v10, v134, 5, 1
	v_or_b32_e32 v2, v0, v10
	v_ashrrev_i32_e32 v3, 31, v2
	v_and_b32_e32 v11, 31, v134
	v_lshlrev_b64 v[6:7], 12, v[2:3]
	v_and_b32_e32 v3, 32, v134
	v_lshlrev_b32_e32 v3, 1, v3
	v_lshlrev_b32_e32 v8, 4, v11
	v_lshl_add_u64 v[6:7], s[36:37], 0, v[6:7]
	v_xor_b32_e32 v96, v8, v3
	v_readfirstlane_b32 s7, v5
	v_lshl_add_u64 v[6:7], v[6:7], 0, v[96:97]
	v_lshl_add_u64 v[6:7], v[6:7], 0, s[20:21]
	s_lshl_b32 s7, s7, 14
	s_add_i32 s8, s7, 0
	s_mov_b32 s9, m0
	s_mov_b32 m0, s8
	s_nop 0
	global_load_lds_dwordx4 v[6:7], off
	s_mov_b32 m0, s9
	v_or_b32_e32 v6, 2, v2
	v_ashrrev_i32_e32 v7, 31, v6
	v_lshlrev_b32_e32 v3, 2, v6
	v_lshlrev_b64 v[8:9], 12, v[6:7]
	v_bitop3_b32 v3, v3, v11, 12 bitop3:0x6c
	v_lshl_add_u64 v[8:9], s[36:37], 0, v[8:9]
	v_lshlrev_b32_e32 v6, 4, v3
	v_mov_b32_e32 v7, v97
	v_lshl_add_u64 v[6:7], v[8:9], 0, v[6:7]
	v_lshl_add_u64 v[6:7], v[6:7], 0, s[20:21]
	s_add_i32 s5, s7, s5
	s_mov_b32 s8, m0
	s_mov_b32 m0, s5
	s_nop 0
	global_load_lds_dwordx4 v[6:7], off
	s_mov_b32 m0, s8
	v_or_b32_e32 v6, 4, v2
	v_ashrrev_i32_e32 v7, 31, v6
	v_lshlrev_b64 v[6:7], 12, v[6:7]
	v_lshl_add_u64 v[6:7], s[36:37], 0, v[6:7]
	v_lshl_add_u64 v[6:7], v[6:7], 0, v[96:97]
	v_lshl_add_u64 v[6:7], v[6:7], 0, s[20:21]
	s_add_i32 s5, s7, s6
	s_mov_b32 s6, m0
	s_mov_b32 m0, s5
	s_nop 0
	global_load_lds_dwordx4 v[6:7], off
	s_mov_b32 m0, s6
	v_or_b32_e32 v6, 6, v2
	v_ashrrev_i32_e32 v7, 31, v6
	v_lshlrev_b32_e32 v3, 2, v6
	v_lshlrev_b64 v[8:9], 12, v[6:7]
	v_bitop3_b32 v3, v3, v11, 12 bitop3:0x6c
	v_lshl_add_u64 v[8:9], s[36:37], 0, v[8:9]
	v_lshlrev_b32_e32 v6, 4, v3
	v_mov_b32_e32 v7, v97
	v_lshl_add_u64 v[6:7], v[8:9], 0, v[6:7]
	v_lshl_add_u64 v[6:7], v[6:7], 0, s[20:21]
	s_add_i32 s5, s7, s18
	s_mov_b32 s6, m0
	s_mov_b32 m0, s5
	s_nop 0
	global_load_lds_dwordx4 v[6:7], off
	s_mov_b32 m0, s6
	v_or_b32_e32 v6, 8, v2
	v_ashrrev_i32_e32 v7, 31, v6
	v_lshlrev_b64 v[6:7], 12, v[6:7]
	v_lshl_add_u64 v[6:7], s[36:37], 0, v[6:7]
	v_lshl_add_u64 v[6:7], v[6:7], 0, v[96:97]
	v_lshl_add_u64 v[6:7], v[6:7], 0, s[20:21]
	s_add_i32 s4, s7, s4
	s_mov_b32 s5, m0
	s_mov_b32 m0, s4
	s_nop 0
	global_load_lds_dwordx4 v[6:7], off
	s_mov_b32 m0, s5
	v_or_b32_e32 v6, 10, v2
	v_ashrrev_i32_e32 v7, 31, v6
	v_lshlrev_b32_e32 v3, 2, v6
	v_lshlrev_b64 v[8:9], 12, v[6:7]
	v_bitop3_b32 v3, v3, v11, 12 bitop3:0x6c
	v_lshl_add_u64 v[8:9], s[36:37], 0, v[8:9]
	v_lshlrev_b32_e32 v6, 4, v3
	v_mov_b32_e32 v7, v97
	v_lshl_add_u64 v[6:7], v[8:9], 0, v[6:7]
	v_lshl_add_u64 v[6:7], v[6:7], 0, s[20:21]
	s_add_i32 s4, s7, s19
	s_mov_b32 s5, m0
	s_mov_b32 m0, s4
	s_nop 0
	global_load_lds_dwordx4 v[6:7], off
	s_mov_b32 m0, s5
	v_or_b32_e32 v6, 12, v2
	v_ashrrev_i32_e32 v7, 31, v6
	v_lshlrev_b64 v[6:7], 12, v[6:7]
	v_lshl_add_u64 v[6:7], s[36:37], 0, v[6:7]
	v_lshl_add_u64 v[6:7], v[6:7], 0, v[96:97]
	v_lshl_add_u64 v[6:7], v[6:7], 0, s[20:21]
	s_add_i32 s4, s7, s41
	s_mov_b32 s5, m0
	s_mov_b32 m0, s4
	s_nop 0
	global_load_lds_dwordx4 v[6:7], off
	s_mov_b32 m0, s5
	v_or_b32_e32 v6, 14, v2
	v_ashrrev_i32_e32 v7, 31, v6
	v_lshlrev_b32_e32 v3, 2, v6
	v_lshlrev_b64 v[8:9], 12, v[6:7]
	v_bitop3_b32 v3, v3, v11, 12 bitop3:0x6c
	v_lshl_add_u64 v[8:9], s[36:37], 0, v[8:9]
	v_lshlrev_b32_e32 v6, 4, v3
	v_mov_b32_e32 v7, v97
	v_lshl_add_u64 v[6:7], v[8:9], 0, v[6:7]
	v_lshl_add_u64 v[6:7], v[6:7], 0, s[20:21]
	s_add_i32 s4, s7, s42
	s_mov_b32 s5, m0
	s_mov_b32 m0, s4
	s_nop 0
	global_load_lds_dwordx4 v[6:7], off
	s_mov_b32 m0, s5
	v_or_b32_e32 v6, 16, v2
	v_ashrrev_i32_e32 v7, 31, v6
	v_lshlrev_b64 v[6:7], 12, v[6:7]
	v_lshl_add_u64 v[6:7], s[36:37], 0, v[6:7]
	v_lshl_add_u64 v[6:7], v[6:7], 0, v[96:97]
	v_lshl_add_u64 v[6:7], v[6:7], 0, s[20:21]
	s_add_i32 s4, s7, s43
	s_mov_b32 s5, m0
	s_mov_b32 m0, s4
	s_nop 0
	global_load_lds_dwordx4 v[6:7], off
	s_mov_b32 m0, s5
	v_or_b32_e32 v6, 18, v2
	v_ashrrev_i32_e32 v7, 31, v6
	v_lshlrev_b32_e32 v3, 2, v6
	v_lshlrev_b64 v[8:9], 12, v[6:7]
	v_bitop3_b32 v3, v3, v11, 12 bitop3:0x6c
	v_lshl_add_u64 v[8:9], s[36:37], 0, v[8:9]
	v_lshlrev_b32_e32 v6, 4, v3
	v_mov_b32_e32 v7, v97
	v_lshl_add_u64 v[6:7], v[8:9], 0, v[6:7]
	v_lshl_add_u64 v[6:7], v[6:7], 0, s[20:21]
	s_add_i32 s4, s7, s44
	s_mov_b32 s5, m0
	s_mov_b32 m0, s4
	s_nop 0
	global_load_lds_dwordx4 v[6:7], off
	s_mov_b32 m0, s5
	v_or_b32_e32 v6, 20, v2
	v_ashrrev_i32_e32 v7, 31, v6
	v_lshlrev_b64 v[6:7], 12, v[6:7]
	v_lshl_add_u64 v[6:7], s[36:37], 0, v[6:7]
	v_lshl_add_u64 v[6:7], v[6:7], 0, v[96:97]
	v_lshl_add_u64 v[6:7], v[6:7], 0, s[20:21]
	s_add_i32 s4, s7, s45
	s_mov_b32 s5, m0
	s_mov_b32 m0, s4
	s_nop 0
	global_load_lds_dwordx4 v[6:7], off
	s_mov_b32 m0, s5
	v_or_b32_e32 v6, 22, v2
	v_ashrrev_i32_e32 v7, 31, v6
	v_lshlrev_b32_e32 v3, 2, v6
	v_lshlrev_b64 v[8:9], 12, v[6:7]
	v_bitop3_b32 v3, v3, v11, 12 bitop3:0x6c
	v_lshl_add_u64 v[8:9], s[36:37], 0, v[8:9]
	v_lshlrev_b32_e32 v6, 4, v3
	v_mov_b32_e32 v7, v97
	v_lshl_add_u64 v[6:7], v[8:9], 0, v[6:7]
	v_lshl_add_u64 v[6:7], v[6:7], 0, s[20:21]
	s_add_i32 s4, s7, s46
	s_mov_b32 s5, m0
	s_mov_b32 m0, s4
	s_nop 0
	global_load_lds_dwordx4 v[6:7], off
	s_mov_b32 m0, s5
	v_or_b32_e32 v6, 24, v2
	v_ashrrev_i32_e32 v7, 31, v6
	v_lshlrev_b64 v[6:7], 12, v[6:7]
	v_lshl_add_u64 v[6:7], s[36:37], 0, v[6:7]
	v_lshl_add_u64 v[6:7], v[6:7], 0, v[96:97]
	v_lshl_add_u64 v[6:7], v[6:7], 0, s[20:21]
	s_add_i32 s4, s7, s47
	s_mov_b32 s5, m0
	s_mov_b32 m0, s4
	s_nop 0
	global_load_lds_dwordx4 v[6:7], off
	s_mov_b32 m0, s5
	v_or_b32_e32 v6, 26, v2
	v_ashrrev_i32_e32 v7, 31, v6
	v_lshlrev_b32_e32 v3, 2, v6
	v_lshlrev_b64 v[8:9], 12, v[6:7]
	v_bitop3_b32 v3, v3, v11, 12 bitop3:0x6c
	v_lshl_add_u64 v[8:9], s[36:37], 0, v[8:9]
	v_lshlrev_b32_e32 v6, 4, v3
	v_mov_b32_e32 v7, v97
	v_lshl_add_u64 v[6:7], v[8:9], 0, v[6:7]
	v_lshl_add_u64 v[6:7], v[6:7], 0, s[20:21]
	s_add_i32 s4, s7, s48
	s_mov_b32 s5, m0
	s_mov_b32 m0, s4
	s_nop 0
	global_load_lds_dwordx4 v[6:7], off
	s_mov_b32 m0, s5
	v_or_b32_e32 v6, 28, v2
	v_ashrrev_i32_e32 v7, 31, v6
	v_lshlrev_b64 v[6:7], 12, v[6:7]
	v_lshl_add_u64 v[6:7], s[36:37], 0, v[6:7]
	v_lshl_add_u64 v[6:7], v[6:7], 0, v[96:97]
	v_or_b32_e32 v2, 30, v2
	v_lshl_add_u64 v[6:7], v[6:7], 0, s[20:21]
	v_ashrrev_i32_e32 v3, 31, v2
	s_add_i32 s4, s7, s49
	s_mov_b32 s5, m0
	s_mov_b32 m0, s4
	s_nop 0
	global_load_lds_dwordx4 v[6:7], off
	s_mov_b32 m0, s5
	v_lshlrev_b64 v[6:7], 12, v[2:3]
	v_lshlrev_b32_e32 v2, 2, v2
	v_bitop3_b32 v2, v2, v11, 12 bitop3:0x6c
	v_lshl_add_u64 v[6:7], s[36:37], 0, v[6:7]
	v_lshlrev_b32_e32 v96, 4, v2
	v_lshl_add_u64 v[2:3], v[6:7], 0, v[96:97]
	v_lshl_add_u64 v[2:3], v[2:3], 0, s[20:21]
	s_waitcnt lgkmcnt(0)
	v_add_f32_e32 v1, v1, v4
	s_add_i32 s7, s7, s50
	s_mov_b32 s4, m0
	s_mov_b32 m0, s7
	s_nop 0
	global_load_lds_dwordx4 v[2:3], off
	s_mov_b32 m0, s4
	s_waitcnt vmcnt(0)
	s_nop 0
	v_div_scale_f32 v2, s[4:5], v1, v1, 1.0
	v_rcp_f32_e32 v3, v2
	s_barrier
	v_cvt_pk_bf16_f32 v120, v45, v48
	v_fma_f32 v4, -v2, v3, 1.0
	v_fmac_f32_e32 v3, v4, v3
	v_div_scale_f32 v4, vcc, 1.0, v1, 1.0
	v_mul_f32_e32 v6, v4, v3
	v_fma_f32 v7, -v2, v6, v4
	v_fmac_f32_e32 v6, v7, v3
	v_fma_f32 v2, -v2, v6, v4
	v_div_fmas_f32 v2, v2, v3, v6
	v_div_fixup_f32 v130, v2, v1, 1.0
	v_ashrrev_i32_e32 v1, 31, v0
	v_lshl_add_u64 v[0:1], s[38:39], 0, v[0:1]
	v_lshlrev_b32_e32 v3, 3, v134
	v_lshlrev_b64 v[0:1], 11, v[0:1]
	v_and_b32_e32 v3, 24, v3
	v_lshl_add_u64 v[0:1], s[26:27], 0, v[0:1]
	v_lshl_add_u64 v[0:1], v[0:1], 0, s[28:29]
	v_lshlrev_b32_e32 v96, 1, v3
	v_bfe_u32 v2, v134, 2, 2
	v_lshl_add_u64 v[132:133], v[0:1], 0, v[96:97]
	v_lshlrev_b32_e32 v0, 1, v134
	v_lshlrev_b32_e32 v136, 6, v2
	v_add_u32_e32 v4, 0, v3
	v_and_b32_e32 v137, 32, v0
	v_lshlrev_b32_e32 v0, 11, v10
	v_lshlrev_b32_e32 v1, 9, v2
	v_or_b32_e32 v139, v136, v137
	v_add3_u32 v138, v4, v0, v1
	v_add_u32_e32 v131, v138, v139
	ds_read_b64_tr_b16 v[0:1], v131
	ds_read_b64_tr_b16 v[2:3], v131 offset:4096
	v_bitop3_b32 v158, v137, v136, 64 bitop3:0x36
	v_add_u32_e32 v143, v138, v158
	s_waitcnt lgkmcnt(0)
	v_mfma_f32_32x32x16_bf16 v[48:63], v[0:3], v[76:79], 0
	ds_read_b64_tr_b16 v[0:1], v143
	ds_read_b64_tr_b16 v[2:3], v143 offset:4096
	v_bitop3_b32 v148, v137, v136, s16 bitop3:0x36
	v_add_u32_e32 v142, v138, v148
	v_cvt_pk_bf16_f32 v126, v32, v35
	v_cvt_pk_bf16_f32 v127, v38, v41
	v_cvt_pk_bf16_f32 v128, v44, v47
	v_cvt_pk_bf16_f32 v118, v33, v36
	v_cvt_pk_bf16_f32 v119, v39, v42
	s_waitcnt lgkmcnt(0)
	v_mfma_f32_32x32x16_bf16 v[32:47], v[0:3], v[76:79], 0
	ds_read_b64_tr_b16 v[0:1], v142
	ds_read_b64_tr_b16 v[2:3], v142 offset:4096
	v_bitop3_b32 v96, v137, v136, s17 bitop3:0x36
	v_add_u32_e32 v141, v138, v96
	v_lshl_add_u32 v140, v5, 11, s51
	v_lshlrev_b32_e32 v5, 6, v134
	v_and_b32_e32 v5, 0x7c0, v5
	v_lshlrev_b32_e32 v6, 3, v10
	s_waitcnt lgkmcnt(0)
	v_mfma_f32_32x32x16_bf16 v[16:31], v[0:3], v[76:79], 0
	ds_read_b64_tr_b16 v[0:1], v141
	ds_read_b64_tr_b16 v[2:3], v141 offset:4096
	ds_read_b64_tr_b16 v[144:145], v131 offset:8192
	ds_read_b64_tr_b16 v[146:147], v131 offset:12288
	v_add3_u32 v135, v140, v5, v6
	v_add_u32_e32 v149, 0x16000, v138
	s_movk_i32 s4, 0x140
	s_add_u32 s0, s0, s94
	s_addc_u32 s1, s1, s70
	s_waitcnt lgkmcnt(0)
	v_mfma_f32_32x32x16_bf16 v[48:63], v[144:147], v[72:75], v[48:63]
	ds_read_b64_tr_b16 v[144:145], v143 offset:8192
	ds_read_b64_tr_b16 v[146:147], v143 offset:12288
	s_mov_b64 s[28:29], 0
	s_waitcnt lgkmcnt(0)
	v_mfma_f32_32x32x16_bf16 v[32:47], v[144:147], v[72:75], v[32:47]
	ds_read_b64_tr_b16 v[144:145], v142 offset:8192
	ds_read_b64_tr_b16 v[146:147], v142 offset:12288
	v_mfma_f32_32x32x16_bf16 v[0:15], v[0:3], v[76:79], 0
	s_waitcnt lgkmcnt(0)
	v_mfma_f32_32x32x16_bf16 v[16:31], v[144:147], v[72:75], v[16:31]
	ds_read_b64_tr_b16 v[144:145], v141 offset:8192
	ds_read_b64_tr_b16 v[146:147], v141 offset:12288
	s_waitcnt lgkmcnt(0)
	v_mfma_f32_32x32x16_bf16 v[0:15], v[144:147], v[72:75], v[0:15]
	ds_read_b64_tr_b16 v[144:145], v131 offset:16384
	ds_read_b64_tr_b16 v[146:147], v131 offset:20480
	s_waitcnt lgkmcnt(0)
	v_mfma_f32_32x32x16_bf16 v[48:63], v[144:147], v[68:71], v[48:63]
	ds_read_b64_tr_b16 v[144:145], v143 offset:16384
	ds_read_b64_tr_b16 v[146:147], v143 offset:20480
	s_waitcnt lgkmcnt(0)
	v_mfma_f32_32x32x16_bf16 v[32:47], v[144:147], v[68:71], v[32:47]
	ds_read_b64_tr_b16 v[144:145], v142 offset:16384
	ds_read_b64_tr_b16 v[146:147], v142 offset:20480
	s_waitcnt lgkmcnt(0)
	v_mfma_f32_32x32x16_bf16 v[16:31], v[144:147], v[68:71], v[16:31]
	ds_read_b64_tr_b16 v[144:145], v141 offset:16384
	ds_read_b64_tr_b16 v[146:147], v141 offset:20480
	s_waitcnt lgkmcnt(0)
	v_mfma_f32_32x32x16_bf16 v[0:15], v[144:147], v[68:71], v[0:15]
	ds_read_b64_tr_b16 v[144:145], v131 offset:24576
	ds_read_b64_tr_b16 v[146:147], v131 offset:28672
	s_waitcnt lgkmcnt(0)
	v_mfma_f32_32x32x16_bf16 v[48:63], v[144:147], v[64:67], v[48:63]
	ds_read_b64_tr_b16 v[144:145], v143 offset:24576
	ds_read_b64_tr_b16 v[146:147], v143 offset:28672
	s_waitcnt lgkmcnt(0)
	v_mfma_f32_32x32x16_bf16 v[32:47], v[144:147], v[64:67], v[32:47]
	ds_read_b64_tr_b16 v[144:145], v142 offset:24576
	ds_read_b64_tr_b16 v[146:147], v142 offset:28672
	s_waitcnt lgkmcnt(0)
	v_mfma_f32_32x32x16_bf16 v[16:31], v[144:147], v[64:67], v[16:31]
	ds_read_b64_tr_b16 v[144:145], v141 offset:24576
	ds_read_b64_tr_b16 v[146:147], v141 offset:28672
	s_waitcnt lgkmcnt(0)
	v_mfma_f32_32x32x16_bf16 v[0:15], v[144:147], v[64:67], v[0:15]
	ds_read_b64_tr_b16 v[144:145], v131 offset:32768
	ds_read_b64_tr_b16 v[146:147], v131 offset:36864
	s_waitcnt lgkmcnt(0)
	v_mfma_f32_32x32x16_bf16 v[48:63], v[144:147], v[92:95], v[48:63]
	ds_read_b64_tr_b16 v[144:145], v143 offset:32768
	ds_read_b64_tr_b16 v[146:147], v143 offset:36864
	s_waitcnt lgkmcnt(0)
	v_mfma_f32_32x32x16_bf16 v[32:47], v[144:147], v[92:95], v[32:47]
	ds_read_b64_tr_b16 v[144:145], v142 offset:32768
	ds_read_b64_tr_b16 v[146:147], v142 offset:36864
	s_waitcnt lgkmcnt(0)
	v_mfma_f32_32x32x16_bf16 v[16:31], v[144:147], v[92:95], v[16:31]
	ds_read_b64_tr_b16 v[144:145], v141 offset:32768
	ds_read_b64_tr_b16 v[146:147], v141 offset:36864
	s_waitcnt lgkmcnt(0)
	v_mfma_f32_32x32x16_bf16 v[0:15], v[144:147], v[92:95], v[0:15]
	ds_read_b64_tr_b16 v[144:145], v131 offset:40960
	ds_read_b64_tr_b16 v[146:147], v131 offset:45056
	s_waitcnt lgkmcnt(0)
	v_mfma_f32_32x32x16_bf16 v[48:63], v[144:147], v[88:91], v[48:63]
	ds_read_b64_tr_b16 v[144:145], v143 offset:40960
	ds_read_b64_tr_b16 v[146:147], v143 offset:45056
	s_waitcnt lgkmcnt(0)
	v_mfma_f32_32x32x16_bf16 v[32:47], v[144:147], v[88:91], v[32:47]
	ds_read_b64_tr_b16 v[144:145], v142 offset:40960
	ds_read_b64_tr_b16 v[146:147], v142 offset:45056
	s_waitcnt lgkmcnt(0)
	v_mfma_f32_32x32x16_bf16 v[16:31], v[144:147], v[88:91], v[16:31]
	ds_read_b64_tr_b16 v[144:145], v141 offset:40960
	ds_read_b64_tr_b16 v[146:147], v141 offset:45056
	s_waitcnt lgkmcnt(0)
	v_mfma_f32_32x32x16_bf16 v[0:15], v[144:147], v[88:91], v[0:15]
	ds_read_b64_tr_b16 v[144:145], v131 offset:49152
	ds_read_b64_tr_b16 v[146:147], v131 offset:53248
	s_waitcnt lgkmcnt(0)
	v_mfma_f32_32x32x16_bf16 v[48:63], v[144:147], v[84:87], v[48:63]
	ds_read_b64_tr_b16 v[144:145], v143 offset:49152
	ds_read_b64_tr_b16 v[146:147], v143 offset:53248
	s_waitcnt lgkmcnt(0)
	v_mfma_f32_32x32x16_bf16 v[32:47], v[144:147], v[84:87], v[32:47]
	ds_read_b64_tr_b16 v[144:145], v142 offset:49152
	ds_read_b64_tr_b16 v[146:147], v142 offset:53248
	s_waitcnt lgkmcnt(0)
	v_mfma_f32_32x32x16_bf16 v[16:31], v[144:147], v[84:87], v[16:31]
	ds_read_b64_tr_b16 v[144:145], v141 offset:49152
	ds_read_b64_tr_b16 v[146:147], v141 offset:53248
	s_waitcnt lgkmcnt(0)
	v_mfma_f32_32x32x16_bf16 v[0:15], v[144:147], v[84:87], v[0:15]
	ds_read_b64_tr_b16 v[144:145], v131 offset:57344
	ds_read_b64_tr_b16 v[146:147], v131 offset:61440
	s_waitcnt lgkmcnt(0)
	v_mfma_f32_32x32x16_bf16 v[48:63], v[144:147], v[80:83], v[48:63]
	ds_read_b64_tr_b16 v[144:145], v143 offset:57344
	ds_read_b64_tr_b16 v[146:147], v143 offset:61440
	s_waitcnt lgkmcnt(0)
	v_mfma_f32_32x32x16_bf16 v[32:47], v[144:147], v[80:83], v[32:47]
	ds_read_b64_tr_b16 v[144:145], v142 offset:57344
	ds_read_b64_tr_b16 v[146:147], v142 offset:61440
	s_waitcnt lgkmcnt(0)
	v_mfma_f32_32x32x16_bf16 v[16:31], v[144:147], v[80:83], v[16:31]
	ds_read_b64_tr_b16 v[142:143], v141 offset:57344
	ds_read_b64_tr_b16 v[144:145], v141 offset:61440
	v_add_u32_e32 v141, 0x11000, v138
	s_waitcnt lgkmcnt(0)
	v_mfma_f32_32x32x16_bf16 v[0:15], v[142:145], v[80:83], v[0:15]
	v_add_u32_e32 v142, 0x10000, v138
	v_add_u32_e32 v143, v142, v139
	ds_read_b64_tr_b16 v[144:145], v143
	v_add_u32_e32 v143, v141, v139
	ds_read_b64_tr_b16 v[146:147], v143
	v_add_u32_e32 v143, v142, v158
	s_waitcnt lgkmcnt(0)
	v_mfma_f32_32x32x16_bf16 v[48:63], v[144:147], v[110:113], v[48:63]
	ds_read_b64_tr_b16 v[144:145], v143
	v_add_u32_e32 v143, v141, v158
	ds_read_b64_tr_b16 v[146:147], v143
	v_add_u32_e32 v143, v142, v148
	s_waitcnt lgkmcnt(0)
	v_mfma_f32_32x32x16_bf16 v[32:47], v[144:147], v[110:113], v[32:47]
	ds_read_b64_tr_b16 v[144:145], v143
	v_add_u32_e32 v143, v141, v148
	ds_read_b64_tr_b16 v[146:147], v143
	v_add_u32_e32 v143, v142, v96
	s_waitcnt lgkmcnt(0)
	v_mfma_f32_32x32x16_bf16 v[16:31], v[144:147], v[110:113], v[16:31]
	ds_read_b64_tr_b16 v[144:145], v143
	v_add_u32_e32 v143, v141, v96
	ds_read_b64_tr_b16 v[146:147], v143
	v_add_u32_e32 v143, 0x13000, v138
	s_waitcnt lgkmcnt(0)
	v_mfma_f32_32x32x16_bf16 v[0:15], v[144:147], v[110:113], v[0:15]
	v_add_u32_e32 v144, 0x12000, v138
	v_add_u32_e32 v145, v144, v139
	ds_read_b64_tr_b16 v[150:151], v145
	v_add_u32_e32 v145, v143, v139
	ds_read_b64_tr_b16 v[152:153], v145
	v_add_u32_e32 v145, v144, v158
	v_add_u32_e32 v146, 0x14000, v138
	s_waitcnt lgkmcnt(0)
	v_mfma_f32_32x32x16_bf16 v[48:63], v[150:153], v[106:109], v[48:63]
	ds_read_b64_tr_b16 v[150:151], v145
	v_add_u32_e32 v145, v143, v158
	ds_read_b64_tr_b16 v[152:153], v145
	v_add_u32_e32 v145, v144, v148
	v_add_u32_e32 v147, v146, v139
	s_waitcnt lgkmcnt(0)
	v_mfma_f32_32x32x16_bf16 v[32:47], v[150:153], v[106:109], v[32:47]
	ds_read_b64_tr_b16 v[150:151], v145
	v_add_u32_e32 v145, v143, v148
	ds_read_b64_tr_b16 v[152:153], v145
	v_add_u32_e32 v145, v144, v96
	s_waitcnt lgkmcnt(0)
	v_mfma_f32_32x32x16_bf16 v[16:31], v[150:153], v[106:109], v[16:31]
	ds_read_b64_tr_b16 v[150:151], v145
	v_add_u32_e32 v145, v143, v96
	ds_read_b64_tr_b16 v[152:153], v145
	v_add_u32_e32 v145, 0x15000, v138
	s_waitcnt lgkmcnt(0)
	v_mfma_f32_32x32x16_bf16 v[0:15], v[150:153], v[106:109], v[0:15]
	ds_read_b64_tr_b16 v[150:151], v147
	v_add_u32_e32 v147, v145, v139
	ds_read_b64_tr_b16 v[152:153], v147
	v_add_u32_e32 v147, v146, v158
	s_waitcnt lgkmcnt(0)
	v_mfma_f32_32x32x16_bf16 v[48:63], v[150:153], v[102:105], v[48:63]
	ds_read_b64_tr_b16 v[150:151], v147
	v_add_u32_e32 v147, v145, v158
	ds_read_b64_tr_b16 v[152:153], v147
	v_add_u32_e32 v147, v146, v148
	s_waitcnt lgkmcnt(0)
	v_mfma_f32_32x32x16_bf16 v[32:47], v[150:153], v[102:105], v[32:47]
	ds_read_b64_tr_b16 v[150:151], v147
	v_add_u32_e32 v147, v145, v148
	ds_read_b64_tr_b16 v[152:153], v147
	v_add_u32_e32 v147, v146, v96
	s_waitcnt lgkmcnt(0)
	v_mfma_f32_32x32x16_bf16 v[16:31], v[150:153], v[102:105], v[16:31]
	ds_read_b64_tr_b16 v[150:151], v147
	v_add_u32_e32 v147, v145, v96
	ds_read_b64_tr_b16 v[152:153], v147
	v_add_u32_e32 v147, 0x17000, v138
	s_waitcnt lgkmcnt(0)
	v_mfma_f32_32x32x16_bf16 v[0:15], v[150:153], v[102:105], v[0:15]
	v_add_u32_e32 v150, v149, v139
	v_add_u32_e32 v152, v147, v139
	ds_read_b64_tr_b16 v[150:151], v150
	ds_read_b64_tr_b16 v[152:153], v152
	s_waitcnt lgkmcnt(0)
	v_mfma_f32_32x32x16_bf16 v[48:63], v[150:153], v[98:101], v[48:63]
	v_add_u32_e32 v150, v149, v158
	v_add_u32_e32 v152, v147, v158
	ds_read_b64_tr_b16 v[150:151], v150
	ds_read_b64_tr_b16 v[152:153], v152
	s_waitcnt lgkmcnt(0)
	v_mfma_f32_32x32x16_bf16 v[32:47], v[150:153], v[98:101], v[32:47]
	v_add_u32_e32 v150, v149, v148
	v_add_u32_e32 v152, v147, v148
	ds_read_b64_tr_b16 v[150:151], v150
	ds_read_b64_tr_b16 v[152:153], v152
	s_waitcnt lgkmcnt(0)
	v_mfma_f32_32x32x16_bf16 v[16:31], v[150:153], v[98:101], v[16:31]
	v_add_u32_e32 v150, v149, v96
	v_add_u32_e32 v152, v147, v96
	ds_read_b64_tr_b16 v[150:151], v150
	ds_read_b64_tr_b16 v[152:153], v152
	s_waitcnt lgkmcnt(0)
	v_mfma_f32_32x32x16_bf16 v[0:15], v[150:153], v[98:101], v[0:15]
	v_add_u32_e32 v151, 0x18000, v138
	v_add_u32_e32 v150, 0x19000, v138
	v_add_u32_e32 v152, v151, v139
	v_add_u32_e32 v154, v150, v139
	ds_read_b64_tr_b16 v[152:153], v152
	ds_read_b64_tr_b16 v[154:155], v154
	s_waitcnt lgkmcnt(0)
	v_mfma_f32_32x32x16_bf16 v[48:63], v[152:155], v[126:129], v[48:63]
	v_add_u32_e32 v152, v151, v158
	v_add_u32_e32 v154, v150, v158
	ds_read_b64_tr_b16 v[152:153], v152
	ds_read_b64_tr_b16 v[154:155], v154
	s_waitcnt lgkmcnt(0)
	v_mfma_f32_32x32x16_bf16 v[32:47], v[152:155], v[126:129], v[32:47]
	v_add_u32_e32 v152, v151, v148
	v_add_u32_e32 v154, v150, v148
	ds_read_b64_tr_b16 v[152:153], v152
	ds_read_b64_tr_b16 v[154:155], v154
	s_waitcnt lgkmcnt(0)
	v_mfma_f32_32x32x16_bf16 v[16:31], v[152:155], v[126:129], v[16:31]
	v_add_u32_e32 v152, v151, v96
	v_add_u32_e32 v154, v150, v96
	ds_read_b64_tr_b16 v[152:153], v152
	ds_read_b64_tr_b16 v[154:155], v154
	s_waitcnt lgkmcnt(0)
	v_mfma_f32_32x32x16_bf16 v[0:15], v[152:155], v[126:129], v[0:15]
	v_add_u32_e32 v153, 0x1a000, v138
	v_add_u32_e32 v152, 0x1b000, v138
	v_add_u32_e32 v154, v153, v139
	v_add_u32_e32 v156, v152, v139
	ds_read_b64_tr_b16 v[154:155], v154
	ds_read_b64_tr_b16 v[156:157], v156
	s_waitcnt lgkmcnt(0)
	v_mfma_f32_32x32x16_bf16 v[48:63], v[154:157], v[122:125], v[48:63]
	v_add_u32_e32 v154, v153, v158
	v_add_u32_e32 v156, v152, v158
	ds_read_b64_tr_b16 v[154:155], v154
	ds_read_b64_tr_b16 v[156:157], v156
	s_waitcnt lgkmcnt(0)
	v_mfma_f32_32x32x16_bf16 v[32:47], v[154:157], v[122:125], v[32:47]
	v_add_u32_e32 v154, v153, v148
	v_add_u32_e32 v156, v152, v148
	ds_read_b64_tr_b16 v[154:155], v154
	ds_read_b64_tr_b16 v[156:157], v156
	s_waitcnt lgkmcnt(0)
	v_mfma_f32_32x32x16_bf16 v[16:31], v[154:157], v[122:125], v[16:31]
	v_add_u32_e32 v154, v153, v96
	v_add_u32_e32 v156, v152, v96
	ds_read_b64_tr_b16 v[154:155], v154
	ds_read_b64_tr_b16 v[156:157], v156
	s_waitcnt lgkmcnt(0)
	v_mfma_f32_32x32x16_bf16 v[0:15], v[154:157], v[122:125], v[0:15]
	v_add_u32_e32 v155, 0x1c000, v138
	v_add_u32_e32 v154, 0x1d000, v138
	v_add_u32_e32 v156, v155, v139
	ds_read_b64_tr_b16 v[160:161], v156
	v_add_u32_e32 v156, v154, v139
	ds_read_b64_tr_b16 v[162:163], v156
	v_add_u32_e32 v156, v155, v158
	s_waitcnt lgkmcnt(0)
	v_mfma_f32_32x32x16_bf16 v[48:63], v[160:163], v[118:121], v[48:63]
	ds_read_b64_tr_b16 v[160:161], v156
	v_add_u32_e32 v156, v154, v158
	ds_read_b64_tr_b16 v[162:163], v156
	v_add_u32_e32 v156, v155, v148
	v_add_u32_e32 v157, 0x1e000, v138
	v_add_u32_e32 v159, v157, v139
	s_waitcnt lgkmcnt(0)
	v_mfma_f32_32x32x16_bf16 v[32:47], v[160:163], v[118:121], v[32:47]
	ds_read_b64_tr_b16 v[160:161], v156
	v_add_u32_e32 v156, v154, v148
	ds_read_b64_tr_b16 v[162:163], v156
	v_add_u32_e32 v156, v155, v96
	s_waitcnt lgkmcnt(0)
	v_mfma_f32_32x32x16_bf16 v[16:31], v[160:163], v[118:121], v[16:31]
	ds_read_b64_tr_b16 v[160:161], v156
	v_add_u32_e32 v156, v154, v96
	ds_read_b64_tr_b16 v[162:163], v156
	v_add_u32_e32 v156, 0x1f000, v138
	s_waitcnt lgkmcnt(0)
	v_mfma_f32_32x32x16_bf16 v[0:15], v[160:163], v[118:121], v[0:15]
	ds_read_b64_tr_b16 v[160:161], v159
	v_add_u32_e32 v159, v156, v139
	ds_read_b64_tr_b16 v[162:163], v159
	v_add_u32_e32 v159, v157, v158
	v_add_u32_e32 v158, v156, v158
	s_waitcnt lgkmcnt(0)
	v_mfma_f32_32x32x16_bf16 v[48:63], v[160:163], v[114:117], v[48:63]
	ds_read_b64_tr_b16 v[160:161], v159
	ds_read_b64_tr_b16 v[162:163], v158
	v_add_u32_e32 v158, v157, v148
	v_add_u32_e32 v148, v156, v148
	ds_read_b64_tr_b16 v[158:159], v158
	s_nop 6
	v_pk_mul_f32 v[48:49], v[130:131], v[48:49] op_sel_hi:[0,1]
	s_waitcnt lgkmcnt(1)
	v_mfma_f32_32x32x16_bf16 v[32:47], v[160:163], v[114:117], v[32:47]
	ds_read_b64_tr_b16 v[160:161], v148
	v_add_u32_e32 v148, v157, v96
	v_add_u32_e32 v96, v156, v96
	v_bfe_u32 v162, v134, 2, 4
	v_mul_f32_e64 v50, v130, v50
	v_mul_f32_e64 v51, v130, v51
	v_cvt_pk_bf16_f32 v48, v48, v49
	v_cvt_pk_bf16_f32 v49, v50, v51
	s_waitcnt lgkmcnt(0)
	v_mfma_f32_32x32x16_bf16 v[16:31], v[158:161], v[114:117], v[16:31]
	ds_read_b64_tr_b16 v[158:159], v148
	ds_read_b64_tr_b16 v[160:161], v96
	v_xor_b32_e32 v148, v162, v134
	v_lshlrev_b32_e32 v148, 4, v148
	v_lshlrev_b32_e32 v96, 6, v162
	v_and_b32_e32 v163, 48, v148
	v_lshlrev_b32_e32 v50, 4, v134
	v_add3_u32 v148, v140, v96, v163
	v_and_b32_e32 v96, 48, v50
	s_waitcnt lgkmcnt(0)
	v_mfma_f32_32x32x16_bf16 v[0:15], v[158:161], v[114:117], v[0:15]
	v_add_u32_e32 v158, v135, v96
	ds_write_b64 v158, v[48:49]
	v_mul_f32_e64 v48, v130, v52
	v_mul_f32_e64 v49, v130, v53
	v_mul_f32_e64 v50, v130, v54
	v_mul_f32_e64 v51, v130, v55
	v_cvt_pk_bf16_f32 v48, v48, v49
	v_cvt_pk_bf16_f32 v49, v50, v51
	v_xad_u32 v159, v96, 16, v135
	ds_write_b64 v159, v[48:49]
	v_pk_mul_f32 v[48:49], v[130:131], v[56:57] op_sel_hi:[0,1]
	v_pk_mul_f32 v[50:51], v[130:131], v[58:59] op_sel_hi:[0,1]
	v_cvt_pk_bf16_f32 v48, v48, v49
	v_cvt_pk_bf16_f32 v49, v50, v51
	v_xad_u32 v160, v96, 32, v135
	ds_write_b64 v160, v[48:49]
	v_pk_mul_f32 v[48:49], v[130:131], v[60:61] op_sel_hi:[0,1]
	v_pk_mul_f32 v[50:51], v[130:131], v[62:63] op_sel_hi:[0,1]
	v_cvt_pk_bf16_f32 v48, v48, v49
	v_cvt_pk_bf16_f32 v49, v50, v51
	v_xad_u32 v161, v96, 48, v135
	ds_write_b64 v161, v[48:49]
	ds_read_b128 v[48:51], v148
	v_lshlrev_b32_e32 v96, 11, v162
	v_lshl_add_u64 v[134:135], v[132:133], 0, v[96:97]
	v_or_b32_e32 v52, 16, v162
	v_pk_mul_f32 v[32:33], v[130:131], v[32:33] op_sel_hi:[0,1]
	s_waitcnt lgkmcnt(0)
	global_store_dwordx4 v[134:135], v[48:51], off sc1
	v_pk_mul_f32 v[34:35], v[130:131], v[34:35] op_sel_hi:[0,1]
	v_cvt_pk_bf16_f32 v32, v32, v33
	v_lshlrev_b32_e32 v48, 6, v52
	v_add3_u32 v140, v140, v48, v163
	v_cvt_pk_bf16_f32 v33, v34, v35
	ds_read_b128 v[48:51], v140
	ds_write_b64 v158, v[32:33]
	v_pk_mul_f32 v[32:33], v[130:131], v[36:37] op_sel_hi:[0,1]
	v_pk_mul_f32 v[34:35], v[130:131], v[38:39] op_sel_hi:[0,1]
	v_cvt_pk_bf16_f32 v32, v32, v33
	v_cvt_pk_bf16_f32 v33, v34, v35
	ds_write_b64 v159, v[32:33]
	v_pk_mul_f32 v[32:33], v[130:131], v[40:41] op_sel_hi:[0,1]
	v_pk_mul_f32 v[34:35], v[130:131], v[42:43] op_sel_hi:[0,1]
	v_cvt_pk_bf16_f32 v32, v32, v33
	v_cvt_pk_bf16_f32 v33, v34, v35
	ds_write_b64 v160, v[32:33]
	v_pk_mul_f32 v[32:33], v[130:131], v[44:45] op_sel_hi:[0,1]
	v_pk_mul_f32 v[34:35], v[130:131], v[46:47] op_sel_hi:[0,1]
	v_cvt_pk_bf16_f32 v32, v32, v33
	v_cvt_pk_bf16_f32 v33, v34, v35
	ds_write_b64 v161, v[32:33]
	ds_read_b128 v[32:35], v148
	v_pk_mul_f32 v[16:17], v[130:131], v[16:17] op_sel_hi:[0,1]
	v_pk_mul_f32 v[18:19], v[130:131], v[18:19] op_sel_hi:[0,1]
	v_cvt_pk_bf16_f32 v16, v16, v17
	v_cvt_pk_bf16_f32 v17, v18, v19
	s_waitcnt lgkmcnt(0)
	global_store_dwordx4 v[134:135], v[32:35], off offset:64 sc1
	ds_read_b128 v[32:35], v140
	ds_write_b64 v158, v[16:17]
	v_pk_mul_f32 v[16:17], v[130:131], v[20:21] op_sel_hi:[0,1]
	v_pk_mul_f32 v[18:19], v[130:131], v[22:23] op_sel_hi:[0,1]
	v_cvt_pk_bf16_f32 v16, v16, v17
	v_cvt_pk_bf16_f32 v17, v18, v19
	ds_write_b64 v159, v[16:17]
	v_pk_mul_f32 v[16:17], v[130:131], v[24:25] op_sel_hi:[0,1]
	v_pk_mul_f32 v[18:19], v[130:131], v[26:27] op_sel_hi:[0,1]
	v_cvt_pk_bf16_f32 v16, v16, v17
	v_cvt_pk_bf16_f32 v17, v18, v19
	ds_write_b64 v160, v[16:17]
	v_pk_mul_f32 v[16:17], v[130:131], v[28:29] op_sel_hi:[0,1]
	v_pk_mul_f32 v[18:19], v[130:131], v[30:31] op_sel_hi:[0,1]
	v_cvt_pk_bf16_f32 v16, v16, v17
	v_cvt_pk_bf16_f32 v17, v18, v19
	ds_write_b64 v161, v[16:17]
	ds_read_b128 v[16:19], v148
	v_pk_mul_f32 v[0:1], v[130:131], v[0:1] op_sel_hi:[0,1]
	v_pk_mul_f32 v[2:3], v[130:131], v[2:3] op_sel_hi:[0,1]
	v_cvt_pk_bf16_f32 v0, v0, v1
	v_cvt_pk_bf16_f32 v1, v2, v3
	s_waitcnt lgkmcnt(0)
	global_store_dwordx4 v[134:135], v[16:19], off offset:128 sc1
	ds_read_b128 v[16:19], v140
	ds_write_b64 v158, v[0:1]
	v_pk_mul_f32 v[0:1], v[130:131], v[4:5] op_sel_hi:[0,1]
	v_pk_mul_f32 v[2:3], v[130:131], v[6:7] op_sel_hi:[0,1]
	v_cvt_pk_bf16_f32 v0, v0, v1
	v_cvt_pk_bf16_f32 v1, v2, v3
	ds_write_b64 v159, v[0:1]
	v_pk_mul_f32 v[0:1], v[130:131], v[8:9] op_sel_hi:[0,1]
	v_pk_mul_f32 v[2:3], v[130:131], v[10:11] op_sel_hi:[0,1]
	v_cvt_pk_bf16_f32 v0, v0, v1
	v_cvt_pk_bf16_f32 v1, v2, v3
	ds_write_b64 v160, v[0:1]
	v_pk_mul_f32 v[0:1], v[130:131], v[12:13] op_sel_hi:[0,1]
	v_pk_mul_f32 v[2:3], v[130:131], v[14:15] op_sel_hi:[0,1]
	v_cvt_pk_bf16_f32 v0, v0, v1
	v_cvt_pk_bf16_f32 v1, v2, v3
	ds_write_b64 v161, v[0:1]
	ds_read_b128 v[0:3], v148
	v_lshlrev_b32_e32 v96, 11, v52
	v_lshl_add_u64 v[132:133], v[132:133], 0, v[96:97]
	global_store_dwordx4 v[132:133], v[48:51], off sc1
	global_store_dwordx4 v[132:133], v[32:35], off offset:64 sc1
	s_waitcnt lgkmcnt(0)
	global_store_dwordx4 v[134:135], v[0:3], off offset:192 sc1
	ds_read_b128 v[0:3], v140
	global_store_dwordx4 v[132:133], v[16:19], off offset:128 sc1
	v_bitop3_b32 v163, v137, v136, s4 bitop3:0x36
	v_add_u32_e32 v165, v138, v163
	s_movk_i32 s4, 0x180
	s_waitcnt lgkmcnt(0)
	global_store_dwordx4 v[132:133], v[0:3], off offset:192 sc1
	ds_read_b64_tr_b16 v[0:1], v131 offset:256
	ds_read_b64_tr_b16 v[2:3], v131 offset:4352
	s_waitcnt lgkmcnt(0)
	v_mfma_f32_32x32x16_bf16 v[48:63], v[0:3], v[76:79], 0
	ds_read_b64_tr_b16 v[0:1], v165
	ds_read_b64_tr_b16 v[2:3], v165 offset:4096
	v_or_b32_e32 v162, 0x100, v139
	v_bitop3_b32 v139, v137, v136, s4 bitop3:0x36
	v_add_u32_e32 v164, v138, v139
	s_movk_i32 s4, 0x1c0
	v_bitop3_b32 v96, v137, v136, s4 bitop3:0x36
	v_add_u32_e32 v136, v138, v96
	s_waitcnt lgkmcnt(0)
	v_mfma_f32_32x32x16_bf16 v[32:47], v[0:3], v[76:79], 0
	ds_read_b64_tr_b16 v[0:1], v164
	ds_read_b64_tr_b16 v[2:3], v164 offset:4096
	s_waitcnt lgkmcnt(0)
	v_mfma_f32_32x32x16_bf16 v[16:31], v[0:3], v[76:79], 0
	ds_read_b64_tr_b16 v[0:1], v136
	ds_read_b64_tr_b16 v[2:3], v136 offset:4096
	s_waitcnt lgkmcnt(0)
	v_mfma_f32_32x32x16_bf16 v[0:15], v[0:3], v[76:79], 0
	ds_read_b64_tr_b16 v[76:77], v131 offset:8448
	ds_read_b64_tr_b16 v[78:79], v131 offset:12544
	s_waitcnt lgkmcnt(0)
	v_mfma_f32_32x32x16_bf16 v[48:63], v[76:79], v[72:75], v[48:63]
	ds_read_b64_tr_b16 v[76:77], v165 offset:8192
	ds_read_b64_tr_b16 v[78:79], v165 offset:12288
	s_waitcnt lgkmcnt(0)
	v_mfma_f32_32x32x16_bf16 v[32:47], v[76:79], v[72:75], v[32:47]
	ds_read_b64_tr_b16 v[76:77], v164 offset:8192
	ds_read_b64_tr_b16 v[78:79], v164 offset:12288
	s_waitcnt lgkmcnt(0)
	v_mfma_f32_32x32x16_bf16 v[16:31], v[76:79], v[72:75], v[16:31]
	ds_read_b64_tr_b16 v[76:77], v136 offset:8192
	ds_read_b64_tr_b16 v[78:79], v136 offset:12288
	s_waitcnt lgkmcnt(0)
	v_mfma_f32_32x32x16_bf16 v[0:15], v[76:79], v[72:75], v[0:15]
	ds_read_b64_tr_b16 v[72:73], v131 offset:16640
	ds_read_b64_tr_b16 v[74:75], v131 offset:20736
	s_waitcnt lgkmcnt(0)
	v_mfma_f32_32x32x16_bf16 v[48:63], v[72:75], v[68:71], v[48:63]
	ds_read_b64_tr_b16 v[72:73], v165 offset:16384
	ds_read_b64_tr_b16 v[74:75], v165 offset:20480
	s_waitcnt lgkmcnt(0)
	v_mfma_f32_32x32x16_bf16 v[32:47], v[72:75], v[68:71], v[32:47]
	ds_read_b64_tr_b16 v[72:73], v164 offset:16384
	ds_read_b64_tr_b16 v[74:75], v164 offset:20480
	s_waitcnt lgkmcnt(0)
	v_mfma_f32_32x32x16_bf16 v[16:31], v[72:75], v[68:71], v[16:31]
	ds_read_b64_tr_b16 v[72:73], v136 offset:16384
	ds_read_b64_tr_b16 v[74:75], v136 offset:20480
	s_waitcnt lgkmcnt(0)
	v_mfma_f32_32x32x16_bf16 v[0:15], v[72:75], v[68:71], v[0:15]
	ds_read_b64_tr_b16 v[68:69], v131 offset:24832
	ds_read_b64_tr_b16 v[70:71], v131 offset:28928
	s_waitcnt lgkmcnt(0)
	v_mfma_f32_32x32x16_bf16 v[48:63], v[68:71], v[64:67], v[48:63]
	ds_read_b64_tr_b16 v[68:69], v165 offset:24576
	ds_read_b64_tr_b16 v[70:71], v165 offset:28672
	s_waitcnt lgkmcnt(0)
	v_mfma_f32_32x32x16_bf16 v[32:47], v[68:71], v[64:67], v[32:47]
	ds_read_b64_tr_b16 v[68:69], v164 offset:24576
	ds_read_b64_tr_b16 v[70:71], v164 offset:28672
	s_waitcnt lgkmcnt(0)
	v_mfma_f32_32x32x16_bf16 v[16:31], v[68:71], v[64:67], v[16:31]
	ds_read_b64_tr_b16 v[68:69], v136 offset:24576
	ds_read_b64_tr_b16 v[70:71], v136 offset:28672
	s_waitcnt lgkmcnt(0)
	v_mfma_f32_32x32x16_bf16 v[0:15], v[68:71], v[64:67], v[0:15]
	ds_read_b64_tr_b16 v[64:65], v131 offset:33024
	ds_read_b64_tr_b16 v[66:67], v131 offset:37120
	s_waitcnt lgkmcnt(0)
	v_mfma_f32_32x32x16_bf16 v[48:63], v[64:67], v[92:95], v[48:63]
	ds_read_b64_tr_b16 v[64:65], v165 offset:32768
	ds_read_b64_tr_b16 v[66:67], v165 offset:36864
	s_waitcnt lgkmcnt(0)
	v_mfma_f32_32x32x16_bf16 v[32:47], v[64:67], v[92:95], v[32:47]
	ds_read_b64_tr_b16 v[64:65], v164 offset:32768
	ds_read_b64_tr_b16 v[66:67], v164 offset:36864
	s_waitcnt lgkmcnt(0)
	v_mfma_f32_32x32x16_bf16 v[16:31], v[64:67], v[92:95], v[16:31]
	ds_read_b64_tr_b16 v[64:65], v136 offset:32768
	ds_read_b64_tr_b16 v[66:67], v136 offset:36864
	s_waitcnt lgkmcnt(0)
	v_mfma_f32_32x32x16_bf16 v[0:15], v[64:67], v[92:95], v[0:15]
	ds_read_b64_tr_b16 v[64:65], v131 offset:41216
	ds_read_b64_tr_b16 v[66:67], v131 offset:45312
	s_waitcnt lgkmcnt(0)
	v_mfma_f32_32x32x16_bf16 v[48:63], v[64:67], v[88:91], v[48:63]
	ds_read_b64_tr_b16 v[64:65], v165 offset:40960
	ds_read_b64_tr_b16 v[66:67], v165 offset:45056
	s_waitcnt lgkmcnt(0)
	v_mfma_f32_32x32x16_bf16 v[32:47], v[64:67], v[88:91], v[32:47]
	ds_read_b64_tr_b16 v[64:65], v164 offset:40960
	ds_read_b64_tr_b16 v[66:67], v164 offset:45056
	s_waitcnt lgkmcnt(0)
	v_mfma_f32_32x32x16_bf16 v[16:31], v[64:67], v[88:91], v[16:31]
	ds_read_b64_tr_b16 v[64:65], v136 offset:40960
	ds_read_b64_tr_b16 v[66:67], v136 offset:45056
	s_waitcnt lgkmcnt(0)
	v_mfma_f32_32x32x16_bf16 v[0:15], v[64:67], v[88:91], v[0:15]
	ds_read_b64_tr_b16 v[64:65], v131 offset:49408
	ds_read_b64_tr_b16 v[66:67], v131 offset:53504
	s_waitcnt lgkmcnt(0)
	v_mfma_f32_32x32x16_bf16 v[48:63], v[64:67], v[84:87], v[48:63]
	ds_read_b64_tr_b16 v[64:65], v165 offset:49152
	ds_read_b64_tr_b16 v[66:67], v165 offset:53248
	s_waitcnt lgkmcnt(0)
	v_mfma_f32_32x32x16_bf16 v[32:47], v[64:67], v[84:87], v[32:47]
	ds_read_b64_tr_b16 v[64:65], v164 offset:49152
	ds_read_b64_tr_b16 v[66:67], v164 offset:53248
	s_waitcnt lgkmcnt(0)
	v_mfma_f32_32x32x16_bf16 v[16:31], v[64:67], v[84:87], v[16:31]
	ds_read_b64_tr_b16 v[64:65], v136 offset:49152
	ds_read_b64_tr_b16 v[66:67], v136 offset:53248
	s_waitcnt lgkmcnt(0)
	v_mfma_f32_32x32x16_bf16 v[0:15], v[64:67], v[84:87], v[0:15]
	ds_read_b64_tr_b16 v[64:65], v131 offset:57600
	ds_read_b64_tr_b16 v[66:67], v131 offset:61696
	s_waitcnt lgkmcnt(0)
	v_mfma_f32_32x32x16_bf16 v[48:63], v[64:67], v[80:83], v[48:63]
	ds_read_b64_tr_b16 v[64:65], v165 offset:57344
	ds_read_b64_tr_b16 v[66:67], v165 offset:61440
	s_waitcnt lgkmcnt(0)
	v_mfma_f32_32x32x16_bf16 v[32:47], v[64:67], v[80:83], v[32:47]
	ds_read_b64_tr_b16 v[64:65], v164 offset:57344
	ds_read_b64_tr_b16 v[66:67], v164 offset:61440
	s_waitcnt lgkmcnt(0)
	v_mfma_f32_32x32x16_bf16 v[16:31], v[64:67], v[80:83], v[16:31]
	ds_read_b64_tr_b16 v[64:65], v136 offset:57344
	ds_read_b64_tr_b16 v[66:67], v136 offset:61440
	s_waitcnt lgkmcnt(0)
	v_mfma_f32_32x32x16_bf16 v[0:15], v[64:67], v[80:83], v[0:15]
	v_add_u32_e32 v64, v142, v162
	v_add_u32_e32 v66, v141, v162
	ds_read_b64_tr_b16 v[64:65], v64
	ds_read_b64_tr_b16 v[66:67], v66
	s_waitcnt lgkmcnt(0)
	v_mfma_f32_32x32x16_bf16 v[48:63], v[64:67], v[110:113], v[48:63]
	v_add_u32_e32 v64, v142, v163
	v_add_u32_e32 v66, v141, v163
	ds_read_b64_tr_b16 v[64:65], v64
	ds_read_b64_tr_b16 v[66:67], v66
	s_waitcnt lgkmcnt(0)
	v_mfma_f32_32x32x16_bf16 v[32:47], v[64:67], v[110:113], v[32:47]
	v_add_u32_e32 v64, v142, v139
	v_add_u32_e32 v66, v141, v139
	ds_read_b64_tr_b16 v[64:65], v64
	ds_read_b64_tr_b16 v[66:67], v66
	s_waitcnt lgkmcnt(0)
	v_mfma_f32_32x32x16_bf16 v[16:31], v[64:67], v[110:113], v[16:31]
	v_add_u32_e32 v64, v142, v96
	v_add_u32_e32 v66, v141, v96
	ds_read_b64_tr_b16 v[64:65], v64
	ds_read_b64_tr_b16 v[66:67], v66
	s_waitcnt lgkmcnt(0)
	v_mfma_f32_32x32x16_bf16 v[0:15], v[64:67], v[110:113], v[0:15]
	v_add_u32_e32 v64, v144, v162
	v_add_u32_e32 v66, v143, v162
	ds_read_b64_tr_b16 v[64:65], v64
	ds_read_b64_tr_b16 v[66:67], v66
	s_waitcnt lgkmcnt(0)
	v_mfma_f32_32x32x16_bf16 v[48:63], v[64:67], v[106:109], v[48:63]
	v_add_u32_e32 v64, v144, v163
	v_add_u32_e32 v66, v143, v163
	ds_read_b64_tr_b16 v[64:65], v64
	ds_read_b64_tr_b16 v[66:67], v66
	s_waitcnt lgkmcnt(0)
	v_mfma_f32_32x32x16_bf16 v[32:47], v[64:67], v[106:109], v[32:47]
	v_add_u32_e32 v64, v144, v139
	v_add_u32_e32 v66, v143, v139
	ds_read_b64_tr_b16 v[64:65], v64
	ds_read_b64_tr_b16 v[66:67], v66
	s_waitcnt lgkmcnt(0)
	v_mfma_f32_32x32x16_bf16 v[16:31], v[64:67], v[106:109], v[16:31]
	v_add_u32_e32 v64, v144, v96
	v_add_u32_e32 v66, v143, v96
	ds_read_b64_tr_b16 v[64:65], v64
	ds_read_b64_tr_b16 v[66:67], v66
	s_waitcnt lgkmcnt(0)
	v_mfma_f32_32x32x16_bf16 v[0:15], v[64:67], v[106:109], v[0:15]
	v_add_u32_e32 v64, v146, v162
	v_add_u32_e32 v66, v145, v162
	ds_read_b64_tr_b16 v[64:65], v64
	ds_read_b64_tr_b16 v[66:67], v66
	s_waitcnt lgkmcnt(0)
	v_mfma_f32_32x32x16_bf16 v[48:63], v[64:67], v[102:105], v[48:63]
	v_add_u32_e32 v64, v146, v163
	v_add_u32_e32 v66, v145, v163
	ds_read_b64_tr_b16 v[64:65], v64
	ds_read_b64_tr_b16 v[66:67], v66
	s_waitcnt lgkmcnt(0)
	v_mfma_f32_32x32x16_bf16 v[32:47], v[64:67], v[102:105], v[32:47]
	v_add_u32_e32 v64, v146, v139
	v_add_u32_e32 v66, v145, v139
	ds_read_b64_tr_b16 v[64:65], v64
	ds_read_b64_tr_b16 v[66:67], v66
	s_waitcnt lgkmcnt(0)
	v_mfma_f32_32x32x16_bf16 v[16:31], v[64:67], v[102:105], v[16:31]
	v_add_u32_e32 v64, v146, v96
	v_add_u32_e32 v66, v145, v96
	ds_read_b64_tr_b16 v[64:65], v64
	ds_read_b64_tr_b16 v[66:67], v66
	s_waitcnt lgkmcnt(0)
	v_mfma_f32_32x32x16_bf16 v[0:15], v[64:67], v[102:105], v[0:15]
	v_add_u32_e32 v64, v149, v162
	v_add_u32_e32 v66, v147, v162
	ds_read_b64_tr_b16 v[64:65], v64
	ds_read_b64_tr_b16 v[66:67], v66
	s_waitcnt lgkmcnt(0)
	v_mfma_f32_32x32x16_bf16 v[48:63], v[64:67], v[98:101], v[48:63]
	v_add_u32_e32 v64, v149, v163
	v_add_u32_e32 v66, v147, v163
	ds_read_b64_tr_b16 v[64:65], v64
	ds_read_b64_tr_b16 v[66:67], v66
	s_waitcnt lgkmcnt(0)
	v_mfma_f32_32x32x16_bf16 v[32:47], v[64:67], v[98:101], v[32:47]
	v_add_u32_e32 v64, v149, v139
	v_add_u32_e32 v66, v147, v139
	ds_read_b64_tr_b16 v[64:65], v64
	ds_read_b64_tr_b16 v[66:67], v66
	s_waitcnt lgkmcnt(0)
	v_mfma_f32_32x32x16_bf16 v[16:31], v[64:67], v[98:101], v[16:31]
	v_add_u32_e32 v64, v149, v96
	v_add_u32_e32 v66, v147, v96
	ds_read_b64_tr_b16 v[64:65], v64
	ds_read_b64_tr_b16 v[66:67], v66
	s_waitcnt lgkmcnt(0)
	v_mfma_f32_32x32x16_bf16 v[0:15], v[64:67], v[98:101], v[0:15]
	v_add_u32_e32 v64, v151, v162
	v_add_u32_e32 v66, v150, v162
	ds_read_b64_tr_b16 v[64:65], v64
	ds_read_b64_tr_b16 v[66:67], v66
	s_waitcnt lgkmcnt(0)
	v_mfma_f32_32x32x16_bf16 v[48:63], v[64:67], v[126:129], v[48:63]
	v_add_u32_e32 v64, v151, v163
	v_add_u32_e32 v66, v150, v163
	ds_read_b64_tr_b16 v[64:65], v64
	ds_read_b64_tr_b16 v[66:67], v66
	s_waitcnt lgkmcnt(0)
	v_mfma_f32_32x32x16_bf16 v[32:47], v[64:67], v[126:129], v[32:47]
	v_add_u32_e32 v64, v151, v139
	v_add_u32_e32 v66, v150, v139
	ds_read_b64_tr_b16 v[64:65], v64
	ds_read_b64_tr_b16 v[66:67], v66
	s_waitcnt lgkmcnt(0)
	v_mfma_f32_32x32x16_bf16 v[16:31], v[64:67], v[126:129], v[16:31]
	v_add_u32_e32 v64, v151, v96
	v_add_u32_e32 v66, v150, v96
	ds_read_b64_tr_b16 v[64:65], v64
	ds_read_b64_tr_b16 v[66:67], v66
	s_waitcnt lgkmcnt(0)
	v_mfma_f32_32x32x16_bf16 v[0:15], v[64:67], v[126:129], v[0:15]
	v_add_u32_e32 v64, v153, v162
	v_add_u32_e32 v66, v152, v162
	ds_read_b64_tr_b16 v[64:65], v64
	ds_read_b64_tr_b16 v[66:67], v66
	s_waitcnt lgkmcnt(0)
	v_mfma_f32_32x32x16_bf16 v[48:63], v[64:67], v[122:125], v[48:63]
	v_add_u32_e32 v64, v153, v163
	v_add_u32_e32 v66, v152, v163
	ds_read_b64_tr_b16 v[64:65], v64
	ds_read_b64_tr_b16 v[66:67], v66
	s_waitcnt lgkmcnt(0)
	v_mfma_f32_32x32x16_bf16 v[32:47], v[64:67], v[122:125], v[32:47]
	v_add_u32_e32 v64, v153, v139
	v_add_u32_e32 v66, v152, v139
	ds_read_b64_tr_b16 v[64:65], v64
	ds_read_b64_tr_b16 v[66:67], v66
	s_waitcnt lgkmcnt(0)
	v_mfma_f32_32x32x16_bf16 v[16:31], v[64:67], v[122:125], v[16:31]
	v_add_u32_e32 v64, v153, v96
	v_add_u32_e32 v66, v152, v96
	ds_read_b64_tr_b16 v[64:65], v64
	ds_read_b64_tr_b16 v[66:67], v66
	s_waitcnt lgkmcnt(0)
	v_mfma_f32_32x32x16_bf16 v[0:15], v[64:67], v[122:125], v[0:15]
	v_add_u32_e32 v64, v155, v162
	v_add_u32_e32 v66, v154, v162
	ds_read_b64_tr_b16 v[64:65], v64
	ds_read_b64_tr_b16 v[66:67], v66
	s_waitcnt lgkmcnt(0)
	v_mfma_f32_32x32x16_bf16 v[48:63], v[64:67], v[118:121], v[48:63]
	v_add_u32_e32 v64, v155, v163
	v_add_u32_e32 v66, v154, v163
	ds_read_b64_tr_b16 v[64:65], v64
	ds_read_b64_tr_b16 v[66:67], v66
	s_waitcnt lgkmcnt(0)
	v_mfma_f32_32x32x16_bf16 v[32:47], v[64:67], v[118:121], v[32:47]
	v_add_u32_e32 v64, v155, v139
	v_add_u32_e32 v66, v154, v139
	ds_read_b64_tr_b16 v[64:65], v64
	ds_read_b64_tr_b16 v[66:67], v66
	s_waitcnt lgkmcnt(0)
	v_mfma_f32_32x32x16_bf16 v[16:31], v[64:67], v[118:121], v[16:31]
	v_add_u32_e32 v64, v155, v96
	v_add_u32_e32 v66, v154, v96
	ds_read_b64_tr_b16 v[64:65], v64
	ds_read_b64_tr_b16 v[66:67], v66
	s_waitcnt lgkmcnt(0)
	v_mfma_f32_32x32x16_bf16 v[0:15], v[64:67], v[118:121], v[0:15]
	v_add_u32_e32 v64, v157, v162
	v_add_u32_e32 v66, v156, v162
	ds_read_b64_tr_b16 v[64:65], v64
	ds_read_b64_tr_b16 v[66:67], v66
	s_waitcnt lgkmcnt(0)
	v_mfma_f32_32x32x16_bf16 v[48:63], v[64:67], v[114:117], v[48:63]
	v_add_u32_e32 v64, v157, v163
	v_add_u32_e32 v66, v156, v163
	ds_read_b64_tr_b16 v[64:65], v64
	ds_read_b64_tr_b16 v[66:67], v66
	s_nop 7
	v_pk_mul_f32 v[48:49], v[130:131], v[48:49] op_sel_hi:[0,1]
	s_waitcnt lgkmcnt(0)
	v_mfma_f32_32x32x16_bf16 v[32:47], v[64:67], v[114:117], v[32:47]
	v_add_u32_e32 v64, v157, v139
	v_add_u32_e32 v66, v156, v139
	ds_read_b64_tr_b16 v[64:65], v64
	ds_read_b64_tr_b16 v[66:67], v66
	v_mul_f32_e64 v50, v130, v50
	v_mul_f32_e64 v51, v130, v51
	v_cvt_pk_bf16_f32 v48, v48, v49
	v_cvt_pk_bf16_f32 v49, v50, v51
	s_waitcnt lgkmcnt(0)
	v_mfma_f32_32x32x16_bf16 v[16:31], v[64:67], v[114:117], v[16:31]
	v_add_u32_e32 v64, v157, v96
	v_add_u32_e32 v66, v156, v96
	ds_read_b64_tr_b16 v[64:65], v64
	ds_read_b64_tr_b16 v[66:67], v66
	ds_write_b64 v158, v[48:49]
	v_pk_mul_f32 v[48:49], v[130:131], v[52:53] op_sel_hi:[0,1]
	v_pk_mul_f32 v[50:51], v[130:131], v[54:55] op_sel_hi:[0,1]
	v_cvt_pk_bf16_f32 v48, v48, v49
	v_cvt_pk_bf16_f32 v49, v50, v51
	ds_write_b64 v159, v[48:49]
	v_pk_mul_f32 v[48:49], v[130:131], v[56:57] op_sel_hi:[0,1]
	v_pk_mul_f32 v[50:51], v[130:131], v[58:59] op_sel_hi:[0,1]
	v_cvt_pk_bf16_f32 v48, v48, v49
	v_cvt_pk_bf16_f32 v49, v50, v51
	ds_write_b64 v160, v[48:49]
	v_pk_mul_f32 v[48:49], v[130:131], v[60:61] op_sel_hi:[0,1]
	v_pk_mul_f32 v[50:51], v[130:131], v[62:63] op_sel_hi:[0,1]
	v_cvt_pk_bf16_f32 v48, v48, v49
	v_cvt_pk_bf16_f32 v49, v50, v51
	ds_write_b64 v161, v[48:49]
	ds_read_b128 v[48:51], v148
	v_pk_mul_f32 v[32:33], v[130:131], v[32:33] op_sel_hi:[0,1]
	v_pk_mul_f32 v[34:35], v[130:131], v[34:35] op_sel_hi:[0,1]
	v_cvt_pk_bf16_f32 v32, v32, v33
	v_cvt_pk_bf16_f32 v33, v34, v35
	s_waitcnt lgkmcnt(0)
	global_store_dwordx4 v[134:135], v[48:51], off offset:256 sc1
	ds_read_b128 v[48:51], v140
	ds_write_b64 v158, v[32:33]
	v_pk_mul_f32 v[32:33], v[130:131], v[36:37] op_sel_hi:[0,1]
	v_pk_mul_f32 v[34:35], v[130:131], v[38:39] op_sel_hi:[0,1]
	v_cvt_pk_bf16_f32 v32, v32, v33
	v_cvt_pk_bf16_f32 v33, v34, v35
	ds_write_b64 v159, v[32:33]
	v_pk_mul_f32 v[32:33], v[130:131], v[40:41] op_sel_hi:[0,1]
	v_pk_mul_f32 v[34:35], v[130:131], v[42:43] op_sel_hi:[0,1]
	v_cvt_pk_bf16_f32 v32, v32, v33
	v_cvt_pk_bf16_f32 v33, v34, v35
	ds_write_b64 v160, v[32:33]
	v_pk_mul_f32 v[32:33], v[130:131], v[44:45] op_sel_hi:[0,1]
	v_pk_mul_f32 v[34:35], v[130:131], v[46:47] op_sel_hi:[0,1]
	v_cvt_pk_bf16_f32 v32, v32, v33
	v_cvt_pk_bf16_f32 v33, v34, v35
	ds_write_b64 v161, v[32:33]
	ds_read_b128 v[32:35], v148
	v_pk_mul_f32 v[16:17], v[130:131], v[16:17] op_sel_hi:[0,1]
	v_pk_mul_f32 v[18:19], v[130:131], v[18:19] op_sel_hi:[0,1]
	v_cvt_pk_bf16_f32 v16, v16, v17
	v_cvt_pk_bf16_f32 v17, v18, v19
	s_waitcnt lgkmcnt(0)
	global_store_dwordx4 v[134:135], v[32:35], off offset:320 sc1
	ds_read_b128 v[32:35], v140
	ds_write_b64 v158, v[16:17]
	v_pk_mul_f32 v[16:17], v[130:131], v[20:21] op_sel_hi:[0,1]
	v_pk_mul_f32 v[18:19], v[130:131], v[22:23] op_sel_hi:[0,1]
	v_cvt_pk_bf16_f32 v16, v16, v17
	v_cvt_pk_bf16_f32 v17, v18, v19
	v_mfma_f32_32x32x16_bf16 v[0:15], v[64:67], v[114:117], v[0:15]
	ds_write_b64 v159, v[16:17]
	v_mul_f32_e64 v16, v130, v24
	v_mul_f32_e64 v17, v130, v25
	v_mul_f32_e64 v18, v130, v26
	v_mul_f32_e64 v19, v130, v27
	v_cvt_pk_bf16_f32 v16, v16, v17
	v_cvt_pk_bf16_f32 v17, v18, v19
	ds_write_b64 v160, v[16:17]
	v_pk_mul_f32 v[16:17], v[130:131], v[28:29] op_sel_hi:[0,1]
	v_pk_mul_f32 v[18:19], v[130:131], v[30:31] op_sel_hi:[0,1]
	v_cvt_pk_bf16_f32 v16, v16, v17
	v_cvt_pk_bf16_f32 v17, v18, v19
	ds_write_b64 v161, v[16:17]
	ds_read_b128 v[16:19], v148
	v_pk_mul_f32 v[0:1], v[130:131], v[0:1] op_sel_hi:[0,1]
	v_pk_mul_f32 v[2:3], v[130:131], v[2:3] op_sel_hi:[0,1]
	v_cvt_pk_bf16_f32 v0, v0, v1
	v_cvt_pk_bf16_f32 v1, v2, v3
	s_waitcnt lgkmcnt(0)
	global_store_dwordx4 v[134:135], v[16:19], off offset:384 sc1
	ds_read_b128 v[16:19], v140
	ds_write_b64 v158, v[0:1]
	v_pk_mul_f32 v[0:1], v[130:131], v[4:5] op_sel_hi:[0,1]
	v_pk_mul_f32 v[2:3], v[130:131], v[6:7] op_sel_hi:[0,1]
	v_cvt_pk_bf16_f32 v0, v0, v1
	v_cvt_pk_bf16_f32 v1, v2, v3
	ds_write_b64 v159, v[0:1]
	v_pk_mul_f32 v[0:1], v[130:131], v[8:9] op_sel_hi:[0,1]
	v_pk_mul_f32 v[2:3], v[130:131], v[10:11] op_sel_hi:[0,1]
	v_cvt_pk_bf16_f32 v0, v0, v1
	v_cvt_pk_bf16_f32 v1, v2, v3
	ds_write_b64 v160, v[0:1]
	v_pk_mul_f32 v[0:1], v[130:131], v[12:13] op_sel_hi:[0,1]
	v_pk_mul_f32 v[2:3], v[130:131], v[14:15] op_sel_hi:[0,1]
	v_cvt_pk_bf16_f32 v0, v0, v1
	v_cvt_pk_bf16_f32 v1, v2, v3
	ds_write_b64 v161, v[0:1]
	ds_read_b128 v[0:3], v148
	global_store_dwordx4 v[132:133], v[48:51], off offset:256 sc1
	global_store_dwordx4 v[132:133], v[32:35], off offset:320 sc1
	s_waitcnt lgkmcnt(5)
	global_store_dwordx4 v[132:133], v[16:19], off offset:384 sc1
	s_waitcnt lgkmcnt(0)
	global_store_dwordx4 v[134:135], v[0:3], off offset:448 sc1
	ds_read_b128 v[0:3], v140
	s_waitcnt lgkmcnt(0)
	global_store_dwordx4 v[132:133], v[0:3], off offset:448 sc1
	s_barrier
